# v4 plus: SSM chunk top barrier removed (wave-local LDS rows, end-state buffer double-buffered); attention head loop: q-norm gain loads hoisted, next-head q loads issued early with one late wait
# speedup vs baseline: 1.0277x; 1.0085x over previous
; #define LAS __attribute__((address_space(3)))
; __device__ __forceinline__ unsigned cvt_pk_bf16(float lo, float hi) { unsigned r; asm("v_cvt_pk_bf16_f32 %0, %1, %2" : "=v"(r) : "v"(lo), "v"(hi)); return r; }
; __device__ __forceinline__ void attn_prompt_item(kp_t kp, LAS unsigned char* lds, int l, int item, const bf16_t* Z, float* YM, int tid, int lane, int wave) {
;     ...
;         for (int i = 0; i < 4; ++i) { u32x4 w; w.x = cvt_pk_bf16(kv[2 * i][0], kv[2 * i][1]); w.y = cvt_pk_bf16(kv[2 * i][2], kv[2 * i][3]); w.z = cvt_pk_bf16(kv[2 * i + 1][0], kv[2 * i + 1][1]); w.w = cvt_pk_bf16(kv[2 * i + 1][2], kv[2 * i + 1][3]);
;             *(LAS u32x4*)(Ks + r * 144 + (half * 32 + 8 * i) * 2) = w; }
; #pragma unroll
;         for (int i = 0; i < 8; ++i)
; #pragma unroll
;             for (int e = 0; e < 4; e += 2) { const unsigned w = cvt_pk_bf16(vv[i][e], vv[i][e + 1]);
;                 *(LAS bf16_t*)(Vt + (half * 32 + 4 * i + e) * 528 + r * 2) = (bf16_t)(w & 0xffffu); *(LAS bf16_t*)(Vt + (half * 32 + 4 * i + e + 1) * 528 + r * 2) = (bf16_t)(w >> 16); }
;     }
;     __syncthreads();
;     const int kbase = 32 * (wave >> 1);
;     const int d0 = kbase + 4 * fq - qi - 128;
;     const float fd0 = (float)d0;
;     ...
;           for (int ks = 0; ks < 2; ++ks) { const f32x4 g0 = *(const f32x4*)(gq + ks * 32 + fq * 8), g1 = *(const f32x4*)(gq + ks * 32 + fq * 8 + 4);
.LBB0_81:
	s_or_b64 exec, exec, s[0:1]
	s_add_u32 s0, s8, s14
	s_movk_i32 s14, 0x90
	v_lshlrev_b32_e32 v73, 16, v0
	v_and_b32_e32 v75, 0xffff0000, v0
	v_mul_lo_u32 v0, v88, s14
	v_lshlrev_b32_e32 v72, 16, v4
	v_and_b32_e32 v74, 0xffff0000, v4
	v_lshlrev_b32_e32 v81, 16, v2
	v_and_b32_e32 v83, 0xffff0000, v2
	v_add3_u32 v4, 0, v0, v90
	v_cvt_pk_bf16_f32 v0, v68, v69
	v_cvt_pk_bf16_f32 v2, v60, v61
	v_lshlrev_b32_e32 v77, 16, v1
	v_and_b32_e32 v79, 0xffff0000, v1
	v_lshlrev_b32_e32 v85, 16, v3
	v_and_b32_e32 v87, 0xffff0000, v3
	v_cvt_pk_bf16_f32 v1, v70, v71
	v_cvt_pk_bf16_f32 v3, v62, v63
	ds_write_b128 v4, v[0:3]
	v_cvt_pk_bf16_f32 v0, v52, v53
	v_cvt_pk_bf16_f32 v2, v44, v45
	v_cvt_pk_bf16_f32 v1, v54, v55
	v_cvt_pk_bf16_f32 v3, v46, v47
	ds_write_b128 v4, v[0:3] offset:16
	v_cvt_pk_bf16_f32 v0, v40, v41
	v_cvt_pk_bf16_f32 v2, v56, v57
	v_cvt_pk_bf16_f32 v1, v42, v43
	v_cvt_pk_bf16_f32 v3, v58, v59
	ds_write_b128 v4, v[0:3] offset:32
	v_cvt_pk_bf16_f32 v0, v48, v49
	v_cvt_pk_bf16_f32 v2, v64, v65
	v_cvt_pk_bf16_f32 v1, v50, v51
	v_cvt_pk_bf16_f32 v3, v66, v67
	ds_write_b128 v4, v[0:3] offset:48
	v_and_b32_e32 v0, -2, v133
	v_mul_i32_i24_e32 v2, 0x210, v89
	v_cvt_pk_bf16_f32 v1, v32, v33
	v_add3_u32 v0, 0, v2, v0
	ds_write_b16 v0, v1 offset:36864
	ds_write_b16_d16_hi v0, v1 offset:37392
	v_cvt_pk_bf16_f32 v1, v34, v35
	ds_write_b16 v0, v1 offset:37920
	ds_write_b16_d16_hi v0, v1 offset:38448
	v_cvt_pk_bf16_f32 v1, v20, v21
	ds_write_b16 v0, v1 offset:38976
	ds_write_b16_d16_hi v0, v1 offset:39504
	v_cvt_pk_bf16_f32 v1, v22, v23
	ds_write_b16 v0, v1 offset:40032
	ds_write_b16_d16_hi v0, v1 offset:40560
	v_cvt_pk_bf16_f32 v1, v36, v37
	ds_write_b16 v0, v1 offset:41088
	ds_write_b16_d16_hi v0, v1 offset:41616
	v_cvt_pk_bf16_f32 v1, v38, v39
	ds_write_b16 v0, v1 offset:42144
	ds_write_b16_d16_hi v0, v1 offset:42672
	v_cvt_pk_bf16_f32 v1, v28, v29
	ds_write_b16 v0, v1 offset:43200
	ds_write_b16_d16_hi v0, v1 offset:43728
	v_cvt_pk_bf16_f32 v1, v30, v31
	ds_write_b16 v0, v1 offset:44256
	ds_write_b16_d16_hi v0, v1 offset:44784
	v_cvt_pk_bf16_f32 v1, v24, v25
	ds_write_b16 v0, v1 offset:45312
	ds_write_b16_d16_hi v0, v1 offset:45840
	v_cvt_pk_bf16_f32 v1, v26, v27
	ds_write_b16 v0, v1 offset:46368
	ds_write_b16_d16_hi v0, v1 offset:46896
	v_cvt_pk_bf16_f32 v1, v16, v17
	s_addc_u32 s1, s9, 0
	s_lshl_b32 s2, s30, 5
	s_lshl_b32 s3, s31, 5
	ds_write_b16 v0, v1 offset:47424
	ds_write_b16_d16_hi v0, v1 offset:47952
	v_cvt_pk_bf16_f32 v1, v18, v19
	v_writelane_b32 v253, s30, 53
	s_and_b32 s2, s2, 0xfffff800
	s_and_b32 s3, s3, 0x780
	ds_write_b16 v0, v1 offset:48480
	ds_write_b16_d16_hi v0, v1 offset:49008
	v_cvt_pk_bf16_f32 v1, v12, v13
	v_lshrrev_b32_e32 v91, 4, v110
	v_writelane_b32 v253, s31, 54
	s_or_b32 s82, s2, s3
	s_and_b32 s3, s29, 3
	ds_write_b16 v0, v1 offset:49536
	ds_write_b16_d16_hi v0, v1 offset:50064
	v_cvt_pk_bf16_f32 v1, v14, v15
	v_writelane_b32 v253, s29, 55
	s_lshl_b32 s2, s3, 9
	ds_write_b16 v0, v1 offset:50592
	ds_write_b16_d16_hi v0, v1 offset:51120
	v_cvt_pk_bf16_f32 v1, v8, v9
	s_and_b32 s13, s12, 0xffffffe0
	v_lshlrev_b32_e32 v14, 2, v91
	v_mov_b32_e32 v148, s2
	s_lshl_b32 s2, s3, 2
	v_readlane_b32 s4, v253, 38
	ds_write_b16 v0, v1 offset:51648
	ds_write_b16_d16_hi v0, v1 offset:52176
	v_cvt_pk_bf16_f32 v1, v10, v11
	v_or_b32_e32 v12, s13, v14
	v_cmp_lt_i32_e32 vcc, v187, v185
	s_or_b32 s33, s2, 1
	s_add_i32 s2, s4, s2
	ds_write_b16 v0, v1 offset:52704
	ds_write_b16_d16_hi v0, v1 offset:53232
	v_sub_u32_e32 v13, v12, v100
	v_cndmask_b32_e32 v0, v184, v187, vcc
	v_cmp_lt_i32_e32 vcc, v250, v185
	v_lshlrev_b32_e32 v92, 3, v91
	s_lshl_b32 s29, s2, 2
	s_lshl_b32 s3, s3, 10
	v_add_u32_e32 v15, 0xffffff80, v13
	v_lshlrev_b32_e32 v104, 2, v0
	v_cndmask_b32_e32 v0, v184, v250, vcc
	v_cvt_f32_i32_e32 v44, v15
	v_lshlrev_b32_e32 v105, 2, v0
	v_lshlrev_b32_e32 v0, 2, v92
	v_mov_b32_e32 v1, v149
	s_cmp_eq_u32 s6, 0
	v_lshl_add_u64 v[46:47], s[0:1], 0, v[0:1]
	global_load_dwordx4 v[200:203], v[46:47], off
	global_load_dwordx4 v[204:207], v[46:47], off offset:16
	global_load_dwordx4 v[208:211], v[46:47], off offset:128
	global_load_dwordx4 v[212:215], v[46:47], off offset:144
	s_cselect_b64 s[36:37], -1, 0
	s_or_b32 s12, s12, 16
	s_add_i32 s11, s13, 32
	s_add_i32 s10, s13, 48
	s_add_i32 s9, s13, 64
	s_add_i32 s8, s13, 0x50
	s_add_i32 s5, s13, 0x60
	s_add_i32 s4, s13, 0x70
	s_add_i32 s1, s13, 0x80
	s_add_i32 s0, s13, 0x90
	v_lshlrev_b32_e32 v76, 16, v5
	v_and_b32_e32 v78, 0xffff0000, v5
	v_lshlrev_b32_e32 v80, 16, v6
	v_and_b32_e32 v82, 0xffff0000, v6
	v_lshlrev_b32_e32 v84, 16, v7
	v_and_b32_e32 v86, 0xffff0000, v7
	v_or_b32_e32 v1, s13, v102
	v_or_b32_e32 v2, s12, v102
	v_or_b32_e32 v3, s11, v102
	v_or_b32_e32 v4, s10, v102
	v_or_b32_e32 v5, s9, v102
	v_or_b32_e32 v6, s8, v102
	v_or_b32_e32 v7, s5, v102
	v_or_b32_e32 v8, s4, v102
	v_or_b32_e32 v9, s1, v102
	v_or_b32_e32 v10, s0, v102
	v_mul_lo_u32 v1, v1, s14
	v_mul_lo_u32 v2, v2, s14
	v_mul_lo_u32 v3, v3, s14
	v_mul_lo_u32 v4, v4, s14
	v_mul_lo_u32 v5, v5, s14
	v_mul_lo_u32 v6, v6, s14
	v_mul_lo_u32 v7, v7, s14
	v_mul_lo_u32 v8, v8, s14
	v_mul_lo_u32 v9, v9, s14
	v_mul_lo_u32 v10, v10, s14
	s_mov_b32 s14, 2.0
	v_add_f32_e32 v45, 1.0, v44
	s_mov_b32 s15, 0x40400000
	v_pk_add_f32 v[48:49], v[44:45], s[14:15] op_sel_hi:[0,1]
	s_mov_b32 s14, 0x41800000
	s_mov_b32 s15, 0x41880000
	v_pk_add_f32 v[50:51], v[44:45], s[14:15] op_sel_hi:[0,1]
	s_mov_b32 s14, 0x41900000
	s_mov_b32 s15, 0x41980000
	v_pk_add_f32 v[52:53], v[44:45], s[14:15] op_sel_hi:[0,1]
	s_mov_b32 s14, 0x42000000
	s_mov_b32 s15, 0x42040000
	v_pk_add_f32 v[54:55], v[44:45], s[14:15] op_sel_hi:[0,1]
	s_mov_b32 s14, 0x42080000
; __device__ __forceinline__ void attn_prompt_item(kp_t kp, LAS unsigned char* lds, int l, int item, const bf16_t* Z, float* YM, int tid, int lane, int wave) {
;     ...
;             for (int j = 0; j < 4; ++j) { const int dd = d0 + 16 * kt + j;
;                 const bool valid = ((unsigned)(dd + 127) <= 127u);
;                 const float lg = valid ? __builtin_fmaf(slope, fd0 + (float)(16 * kt + j), sc[kt][j]) : -1e30f; sc[kt][j] = lg; m = fmaxf(m, lg); }
;         if (blk == 0) {
;             m = sink;
; #pragma unroll
;             for (int kt = 0; kt < 10; ++kt)
; #pragma unroll
;                 for (int j = 0; j < 4; ++j) { const int kj = kbase + 16 * kt + 4 * fq + j; const float lg = (kj >= 128) ? sc[kt][j] : -1e30f; sc[kt][j] = lg; m = fmaxf(m, lg); }
	s_mov_b32 s15, 0x420c0000
	v_pk_add_f32 v[56:57], v[44:45], s[14:15] op_sel_hi:[0,1]
	s_mov_b32 s14, 0x42400000
	v_add_u32_e32 v16, -1, v13
	s_movk_i32 s22, 0x80
	s_mov_b32 s15, 0x42440000
	v_cmp_gt_u32_e64 s[42:43], s22, v16
	v_add_u32_e32 v16, 15, v13
	v_pk_add_f32 v[58:59], v[44:45], s[14:15] op_sel_hi:[0,1]
	s_mov_b32 s14, 0x42480000
	v_cmp_gt_u32_e64 s[46:47], s22, v16
	v_add_u32_e32 v16, 31, v13
	s_mov_b32 s15, 0x424c0000
	v_cmp_gt_u32_e64 s[50:51], s22, v16
	v_add_u32_e32 v16, 47, v13
	v_pk_add_f32 v[60:61], v[44:45], s[14:15] op_sel_hi:[0,1]
	s_mov_b32 s14, 0x42800000
	v_cmp_gt_u32_e64 s[54:55], s22, v16
	v_add_u32_e32 v16, 63, v13
	s_mov_b32 s15, 0x42820000
	s_movk_i32 s13, 0xff7f
	v_cmp_gt_u32_e64 s[58:59], s22, v16
	v_pk_add_f32 v[62:63], v[44:45], s[14:15] op_sel_hi:[0,1]
	s_mov_b32 s14, 0x42840000
	v_add_u32_e32 v16, 0x4f, v13
	s_movk_i32 s20, 0x7e
	v_cmp_lt_u32_e64 s[40:41], s13, v15
	s_mov_b32 s15, 0x42860000
	v_cmp_gt_u32_e64 s[62:63], s22, v16
	v_add_u32_e32 v16, 0x5f, v13
	v_and_b32_e32 v15, 0xffffff80, v15
	s_movk_i32 s13, 0xff00
	v_cmp_lt_i32_e64 s[6:7], s20, v12
	v_pk_add_f32 v[64:65], v[44:45], s[14:15] op_sel_hi:[0,1]
	s_mov_b32 s14, 0x42a00000
	v_cmp_gt_u32_e64 s[66:67], s22, v16
	v_add_u32_e32 v16, 0x6f, v13
	v_cmp_eq_u32_e64 s[74:75], s13, v15
	v_add_u32_e32 v15, 0x8f, v13
	v_writelane_b32 v253, s6, 56
	s_mov_b32 s15, 0x42a20000
	v_cmp_gt_u32_e64 s[70:71], s22, v16
	v_add_u32_e32 v16, 0x7f, v13
	v_cmp_gt_u32_e64 s[78:79], s22, v15
	v_writelane_b32 v253, s7, 57
	v_cmp_lt_i32_e64 s[6:7], s80, v12
	v_add_u32_e32 v15, 1, v13
	v_pk_add_f32 v[66:67], v[44:45], s[14:15] op_sel_hi:[0,1]
	s_mov_b32 s14, 0x42a40000
	v_cmp_gt_u32_e64 s[72:73], s22, v16
	v_add_u32_e32 v16, 0x90, v13
	v_writelane_b32 v253, s6, 58
	v_cmp_gt_u32_e64 s[86:87], s22, v15
	v_or_b32_e32 v15, 3, v12
	s_mov_b32 s15, 0x42a60000
	v_cmp_gt_u32_e64 s[76:77], s22, v16
	v_writelane_b32 v253, s7, 59
	v_add_u32_e32 v16, 2, v13
	v_cmp_lt_i32_e64 s[6:7], s80, v15
	v_pk_add_f32 v[68:69], v[44:45], s[14:15] op_sel_hi:[0,1]
	s_mov_b32 s14, 0x42c00000
	v_cmp_gt_u32_e64 s[84:85], s22, v16
	v_or_b32_e32 v16, 2, v12
	v_writelane_b32 v253, s6, 60
	s_mov_b32 s15, 0x42c20000
	v_pk_add_f32 v[70:71], v[44:45], s[14:15] op_sel_hi:[0,1]
	v_writelane_b32 v253, s7, 61
	v_cmp_lt_i32_e64 s[6:7], s80, v16
	s_mov_b32 s14, 0x42c40000
	v_or_b32_e32 v15, s12, v14
	v_writelane_b32 v253, s6, 62
	s_mov_b32 s15, 0x42c60000
	v_pk_add_f32 v[88:89], v[44:45], s[14:15] op_sel_hi:[0,1]
	v_writelane_b32 v253, s7, 63
	v_cmp_lt_i32_e64 s[6:7], s20, v15
	s_mov_b32 s14, 0x42e00000
	s_mov_b32 s15, 0x42e20000
	v_writelane_b32 v254, s6, 0
	v_add_u32_e32 v16, 17, v13
	v_pk_add_f32 v[90:91], v[44:45], s[14:15] op_sel_hi:[0,1]
	v_writelane_b32 v254, s7, 1
	v_cmp_lt_i32_e64 s[6:7], s80, v15
	s_mov_b32 s14, 0x42e40000
	v_cmp_gt_u32_e64 s[98:99], s22, v16
	v_writelane_b32 v254, s6, 2
	v_or_b32_e32 v16, 3, v15
	s_mov_b32 s15, 0x42e60000
	v_writelane_b32 v254, s7, 3
	v_cmp_lt_i32_e64 s[6:7], s80, v16
	v_pk_add_f32 v[92:93], v[44:45], s[14:15] op_sel_hi:[0,1]
	s_mov_b32 s14, 0x43020000
	v_or_b32_e32 v15, 2, v15
	v_writelane_b32 v254, s6, 4
	s_mov_b32 s15, 0x43030000
	v_pk_add_f32 v[94:95], v[44:45], s[14:15] op_sel_hi:[0,1]
	v_writelane_b32 v254, s7, 5
	v_cmp_lt_i32_e64 s[6:7], s80, v15
	s_mov_b32 s14, 0x43100000
	v_or_b32_e32 v15, s11, v14
	v_writelane_b32 v254, s6, 6
	s_mov_b32 s15, 0x43110000
	v_pk_add_f32 v[96:97], v[44:45], s[14:15] op_sel_hi:[0,1]
	v_writelane_b32 v254, s7, 7
	v_cmp_lt_i32_e64 s[6:7], s20, v15
	s_mov_b32 s14, 0x43120000
	s_mov_b32 s15, 0x43130000
	v_writelane_b32 v254, s6, 8
	v_add_u32_e32 v16, 33, v13
	v_pk_add_f32 v[98:99], v[44:45], s[14:15] op_sel_hi:[0,1]
	v_writelane_b32 v254, s7, 9
	v_cmp_lt_i32_e64 s[6:7], s80, v15
	v_cmp_gt_u32_e64 s[14:15], s22, v16
	v_or_b32_e32 v16, 3, v15
	v_writelane_b32 v254, s6, 10
	v_or_b32_e32 v15, 2, v15
	v_add_u32_e32 v17, 16, v13
	v_writelane_b32 v254, s7, 11
	v_cmp_lt_i32_e64 s[6:7], s80, v16
	v_add_u32_e32 v16, 49, v13
	v_cmp_gt_u32_e64 s[26:27], s22, v16
	v_writelane_b32 v254, s6, 12
	v_cmp_gt_u32_e64 s[44:45], s22, v17
	v_add_u32_e32 v17, 32, v13
	v_writelane_b32 v254, s7, 13
	v_cmp_lt_i32_e64 s[6:7], s80, v15
	v_or_b32_e32 v15, s10, v14
	v_or_b32_e32 v16, 3, v15
	v_writelane_b32 v254, s6, 14
	v_cmp_gt_u32_e64 s[48:49], s22, v17
	v_add_u32_e32 v17, 48, v13
	v_writelane_b32 v254, s7, 15
	v_cmp_lt_i32_e64 s[6:7], s20, v15
	v_cmp_gt_u32_e64 s[52:53], s22, v17
	v_add_u32_e32 v17, 64, v13
	v_writelane_b32 v254, s6, 16
	v_cmp_gt_u32_e64 s[56:57], s22, v17
	v_add_u32_e32 v17, 0x50, v13
	v_writelane_b32 v254, s7, 17
	v_cmp_lt_i32_e64 s[6:7], s80, v15
	v_or_b32_e32 v15, 2, v15
	v_cmp_gt_u32_e64 s[60:61], s22, v17
	v_writelane_b32 v254, s6, 18
	v_add_u32_e32 v17, 0x60, v13
	v_cmp_gt_u32_e64 s[64:65], s22, v17
	v_writelane_b32 v254, s7, 19
	v_cmp_lt_i32_e64 s[6:7], s80, v16
	v_add_u32_e32 v16, 0x41, v13
	v_add_u32_e32 v17, 0x70, v13
	v_writelane_b32 v254, s6, 20
	v_cmp_gt_u32_e64 s[68:69], s22, v17
	v_add_u32_e32 v17, 18, v13
	v_writelane_b32 v254, s7, 21
	v_cmp_lt_i32_e64 s[6:7], s80, v15
	v_or_b32_e32 v15, s9, v14
	s_movk_i32 s9, 0x7f
	v_writelane_b32 v254, s6, 22
	v_cmp_gt_u32_e64 s[96:97], s22, v17
	v_add_u32_e32 v17, 34, v13
	v_writelane_b32 v254, s7, 23
	v_cmp_lt_i32_e64 s[6:7], s20, v15
	v_cmp_gt_u32_e64 s[12:13], s22, v17
	v_add_u32_e32 v17, 50, v13
	v_writelane_b32 v254, s6, 24
	v_cmp_gt_u32_e64 s[24:25], s22, v17
	v_add_u32_e32 v17, 0x42, v13
	v_writelane_b32 v254, s7, 25
	v_cmp_lt_i32_e64 s[6:7], s80, v15
	v_cmp_gt_u32_e64 s[80:81], s22, v16
	v_or_b32_e32 v16, 3, v15
	v_writelane_b32 v254, s6, 26
	v_or_b32_e32 v15, 2, v15
	v_cmp_gt_u32_e64 s[38:39], s22, v17
	v_writelane_b32 v254, s7, 27
	v_cmp_lt_i32_e64 s[6:7], s9, v16
	v_add_u32_e32 v16, 0x51, v13
	v_cmp_gt_u32_e64 s[92:93], s22, v16
	v_writelane_b32 v254, s6, 28
	v_add_u32_e32 v17, 0x52, v13
	v_cmp_gt_u32_e64 s[90:91], s22, v17
	v_writelane_b32 v254, s7, 29
	v_cmp_lt_i32_e64 s[6:7], s9, v15
	v_or_b32_e32 v15, s8, v14
	v_or_b32_e32 v16, 3, v15
	v_writelane_b32 v254, s6, 30
	v_add_u32_e32 v17, 0x62, v13
	v_cmp_gt_u32_e64 s[10:11], s22, v17
	v_writelane_b32 v254, s7, 31
	v_cmp_lt_i32_e64 s[6:7], s20, v15
	v_add_u32_e32 v17, 0x72, v13
	v_cmp_gt_u32_e64 s[30:31], s22, v17
	v_writelane_b32 v254, s6, 32
	v_add_u32_e32 v17, 0x82, v13
	v_cmp_gt_u32_e64 s[88:89], s22, v17
	v_writelane_b32 v254, s7, 33
	v_cmp_lt_i32_e64 s[6:7], s9, v15
	v_or_b32_e32 v15, 2, v15
	v_lshl_add_u32 v17, v12, 1, 0
	v_writelane_b32 v254, s6, 34
	v_or_b32_e32 v12, 48, v110
	v_mul_u32_u24_e32 v18, 0x210, v12
	v_writelane_b32 v254, s7, 35
	v_cmp_lt_i32_e64 s[6:7], s9, v16
	v_add_u32_e32 v16, 0x61, v13
	v_cmp_gt_u32_e64 s[16:17], s22, v16
	v_writelane_b32 v254, s6, 36
	s_movk_i32 s8, 0x1400
	s_waitcnt lgkmcnt(0)
	v_writelane_b32 v254, s7, 37
	v_cmp_lt_i32_e64 s[6:7], s9, v15
	v_or_b32_e32 v15, s5, v14
	v_or_b32_e32 v16, 3, v15
	v_writelane_b32 v254, s6, 38
	s_barrier
; __device__ __forceinline__ void attn_prompt_item(kp_t kp, LAS unsigned char* lds, int l, int item, const bf16_t* Z, float* YM, int tid, int lane, int wave) {
;     ...
;     const bf16_t* qp = Z + tq * INW + 1024 + kvh * 256 + fq * 8;
;     ...
;     __syncthreads();
;     const int kbase = 32 * (wave >> 1);
;     const int d0 = kbase + 4 * fq - qi - 128;
;     const float fd0 = (float)d0;
	s_nop 0
	v_writelane_b32 v254, s7, 39
	v_cmp_lt_i32_e64 s[6:7], s20, v15
	v_and_b32_e32 v11, 48, v133
	v_add_u32_e32 v0, 0, v11
	v_writelane_b32 v254, s6, 40
	s_mov_b32 s2, s83
	v_add_f32_e32 v106, 0x43000000, v44
	v_writelane_b32 v254, s7, 41
	v_cmp_lt_i32_e64 s[6:7], s9, v15
	v_or_b32_e32 v15, 2, v15
	v_add_f32_e32 v107, 0x43010000, v44
	v_writelane_b32 v254, s6, 42
	v_add_u32_e32 v108, v0, v1
	v_add_u32_e32 v109, v0, v2
	v_writelane_b32 v254, s7, 43
	v_cmp_lt_i32_e64 s[6:7], s9, v16
	v_add_u32_e32 v16, 0x71, v13
	v_cmp_gt_u32_e64 s[34:35], s22, v16
	v_writelane_b32 v254, s6, 44
	v_add_u32_e32 v111, v0, v3
	v_add_u32_e32 v112, v0, v4
	v_writelane_b32 v254, s7, 45
	v_cmp_lt_i32_e64 s[6:7], s9, v15
	v_or_b32_e32 v15, s4, v14
	v_cmp_lt_i32_e64 s[4:5], s20, v15
	v_writelane_b32 v254, s6, 46
	v_or_b32_e32 v16, 3, v15
	v_add_u32_e32 v113, v0, v5
	v_writelane_b32 v254, s7, 47
	v_writelane_b32 v254, s4, 48
	v_add_u32_e32 v114, v0, v6
	v_add_u32_e32 v115, v0, v7
	v_writelane_b32 v254, s5, 49
	v_cmp_lt_i32_e64 s[4:5], s9, v15
	v_or_b32_e32 v15, 2, v15
	v_add_u32_e32 v116, v0, v8
	v_writelane_b32 v254, s4, 50
	v_add_u32_e32 v117, v0, v9
	v_add_u32_e32 v118, v0, v10
	v_writelane_b32 v254, s5, 51
	v_cmp_lt_i32_e64 s[4:5], s9, v16
	v_add_u32_e32 v16, 0x81, v13
	v_cmp_gt_u32_e64 s[94:95], s22, v16
	v_writelane_b32 v254, s4, 52
	v_add_u32_e32 v120, v17, v18
	s_nop 0
	v_writelane_b32 v254, s5, 53
	v_cmp_lt_i32_e64 s[4:5], s9, v15
	v_or_b32_e32 v15, s1, v14
	v_or_b32_e32 v16, 3, v15
	v_writelane_b32 v254, s4, 54
	v_or_b32_e32 v14, s0, v14
	v_cmp_lt_i32_e64 s[0:1], s20, v14
	v_writelane_b32 v254, s5, 55
	v_cmp_lt_i32_e64 s[4:5], s9, v15
	v_writelane_b32 v255, s0, 0
	s_nop 0
	v_writelane_b32 v254, s4, 56
	v_writelane_b32 v255, s1, 1
	v_cmp_lt_i32_e64 s[0:1], s9, v14
	v_writelane_b32 v254, s5, 57
	v_cmp_lt_i32_e64 s[4:5], s20, v15
	v_or_b32_e32 v15, 2, v15
	v_writelane_b32 v255, s0, 2
	v_writelane_b32 v254, s4, 58
	s_nop 0
	v_writelane_b32 v255, s1, 3
	v_writelane_b32 v254, s5, 59
	v_cmp_lt_i32_e64 s[4:5], s9, v16
	v_mul_u32_u24_e32 v16, 0x210, v102
	v_add_u32_e32 v119, v17, v16
	v_writelane_b32 v254, s4, 60
	s_nop 1
	v_writelane_b32 v254, s5, 61
	v_cmp_lt_i32_e64 s[4:5], s9, v15
	v_add_u32_e32 v15, 0x91, v13
	v_add_u32_e32 v13, 0x92, v13
	v_cmp_gt_u32_e64 s[20:21], s22, v13
	v_or_b32_e32 v13, 3, v14
	v_cmp_lt_i32_e64 s[0:1], s9, v13
	v_or_b32_e32 v14, 2, v14
	v_lshl_add_u64 v[12:13], v[100:101], 0, s[82:83]
	v_writelane_b32 v255, s0, 4
	v_cmp_gt_u32_e64 s[22:23], s22, v15
	v_writelane_b32 v254, s4, 62
	v_writelane_b32 v255, s1, 5
	v_cmp_lt_i32_e64 s[0:1], s9, v14
	v_writelane_b32 v254, s5, 63
	s_nop 0
	v_writelane_b32 v255, s0, 6
	s_nop 1
	v_writelane_b32 v255, s1, 7
	v_mad_u64_u32 v[14:15], s[0:1], v12, s8, v[148:149]
	v_readlane_b32 s0, v253, 49
	v_readlane_b32 s1, v253, 50
	s_load_dwordx4 s[4:7], s[0:1], 0xf8
	v_mad_i32_i24 v15, v13, s8, v15
	v_lshlrev_b64 v[12:13], 13, v[12:13]
	v_readlane_b32 s0, v253, 44
	v_or_b32_e32 v14, v14, v11
	v_or3_b32 v12, v12, s3, v11
	v_readlane_b32 s1, v253, 45
	s_waitcnt lgkmcnt(0)
	v_lshl_add_u64 v[100:101], s[6:7], 0, v[14:15]
	s_mov_b64 s[8:9], 0
	v_lshl_add_u64 v[102:103], s[0:1], 0, v[12:13]
	s_waitcnt vmcnt(0)
	s_branch .LBB0_84

; #define LAS __attribute__((address_space(3)))
; __device__ __forceinline__ unsigned cvt_pk_bf16(float lo, float hi) { unsigned r; asm("v_cvt_pk_bf16_f32 %0, %1, %2" : "=v"(r) : "v"(lo), "v"(hi)); return r; }
; __device__ __forceinline__ void attn_prompt_item(kp_t kp, LAS unsigned char* lds, int l, int item, const bf16_t* Z, float* YM, int tid, int lane, int wave) {
;     ...
;         m = fmaxf(m, __shfl_xor(m, 16)); m = fmaxf(m, __shfl_xor(m, 32));
;         float sum = 0.f;
; #pragma unroll
;         for (int kt = 0; kt < 10; ++kt)
; #pragma unroll
;             for (int j = 0; j < 4; ++j) { const float pv = __expf(sc[kt][j] - m); sc[kt][j] = pv; sum += pv; }
;         sum += __shfl_xor(sum, 16); sum += __shfl_xor(sum, 32);
;         const float inv = 1.0f / (sum + __expf(sink - m));
;         f32x4 oc[4];
; #pragma unroll
;         for (int dt = 0; dt < 4; ++dt) oc[dt] = (f32x4){0.f, 0.f, 0.f, 0.f};
; #pragma unroll
;         for (int s5 = 0; s5 < 5; ++s5) {
;             u32x4 w; w.x = cvt_pk_bf16(sc[2 * s5][0], sc[2 * s5][1]); w.y = cvt_pk_bf16(sc[2 * s5][2], sc[2 * s5][3]); w.z = cvt_pk_bf16(sc[2 * s5 + 1][0], sc[2 * s5 + 1][1]); w.w = cvt_pk_bf16(sc[2 * s5 + 1][2], sc[2 * s5 + 1][3]);
;             const bf16x8 pb = __builtin_bit_cast(bf16x8, w);
; #pragma unroll
;             for (int dt = 0; dt < 4; ++dt) { const LAS unsigned char* vr = Vt + (dt * 16 + fr) * 528 + (kbase + 32 * s5 + 4 * fq) * 2;
;                 const u32x2 lo = *(const LAS u32x2*)vr, hi = *(const LAS u32x2*)(vr + 32);
;                 u32x4 av; av.x = lo.x; av.y = lo.y; av.z = hi.x; av.w = hi.y;
;                 oc[dt] = __builtin_amdgcn_mfma_f32_16x16x32_bf16(__builtin_bit_cast(bf16x8, av), pb, oc[dt], 0, 0, 0); } }
.LBB0_83:
	v_max3_f32 v3, v3, v2, v0
	ds_bpermute_b32 v7, v104, v3
	v_max_f32_e32 v3, v3, v3
	s_add_u32 s8, s8, 0x80
	s_addc_u32 s9, s9, 0
	s_add_i32 s33, s33, 1
	s_waitcnt lgkmcnt(0)
	v_max_f32_e32 v7, v7, v7
	v_max_f32_e32 v3, v3, v7
	ds_bpermute_b32 v7, v105, v3
	s_add_u32 s29, s29, 4
	s_addc_u32 s2, s2, 0
	s_cmpk_lg_i32 s8, 0x200
	s_waitcnt lgkmcnt(0)
	v_max_f32_e32 v7, v7, v7
	v_max_f32_e32 v126, v3, v7
	v_sub_f32_e32 v7, v124, v126
	v_mul_f32_e32 v7, 0x3fb8aa3b, v7
	v_exp_f32_e32 v124, v7
	v_sub_f32_e32 v7, v123, v126
	v_mul_f32_e32 v7, 0x3fb8aa3b, v7
	v_exp_f32_e32 v123, v7
	v_sub_f32_e32 v7, v122, v126
	v_mul_f32_e32 v7, 0x3fb8aa3b, v7
	v_exp_f32_e32 v122, v7
	v_sub_f32_e32 v7, v121, v126
	v_mul_f32_e32 v7, 0x3fb8aa3b, v7
	v_exp_f32_e32 v121, v7
	v_sub_f32_e32 v7, v43, v126
	v_mul_f32_e32 v7, 0x3fb8aa3b, v7
	v_exp_f32_e32 v43, v7
	v_sub_f32_e32 v7, v42, v126
	v_mul_f32_e32 v7, 0x3fb8aa3b, v7
	v_exp_f32_e32 v42, v7
	v_sub_f32_e32 v7, v40, v126
	v_mul_f32_e32 v7, 0x3fb8aa3b, v7
	v_exp_f32_e32 v40, v7
	v_sub_f32_e32 v7, v41, v126
	v_mul_f32_e32 v7, 0x3fb8aa3b, v7
	v_exp_f32_e32 v27, v7
	v_sub_f32_e32 v7, v39, v126
	v_mul_f32_e32 v7, 0x3fb8aa3b, v7
	v_exp_f32_e32 v127, v7
	v_sub_f32_e32 v7, v38, v126
	v_mul_f32_e32 v7, 0x3fb8aa3b, v7
	v_exp_f32_e32 v128, v7
	v_sub_f32_e32 v7, v36, v126
	v_mul_f32_e32 v7, 0x3fb8aa3b, v7
	v_exp_f32_e32 v129, v7
	v_sub_f32_e32 v7, v37, v126
	v_mul_f32_e32 v7, 0x3fb8aa3b, v7
	v_exp_f32_e32 v130, v7
	v_sub_f32_e32 v7, v35, v126
	v_mul_f32_e32 v7, 0x3fb8aa3b, v7
	v_exp_f32_e32 v131, v7
	v_sub_f32_e32 v7, v34, v126
	v_mul_f32_e32 v7, 0x3fb8aa3b, v7
	v_exp_f32_e32 v132, v7
	v_sub_f32_e32 v7, v32, v126
	v_sub_f32_e32 v3, v125, v126
	v_mul_f32_e32 v7, 0x3fb8aa3b, v7
	v_mul_f32_e32 v3, 0x3fb8aa3b, v3
	v_exp_f32_e32 v134, v7
	v_sub_f32_e32 v7, v33, v126
	v_exp_f32_e32 v125, v3
	v_mul_f32_e32 v7, 0x3fb8aa3b, v7
	v_exp_f32_e32 v18, v7
	v_sub_f32_e32 v7, v31, v126
	v_mul_f32_e32 v7, 0x3fb8aa3b, v7
	v_exp_f32_e32 v19, v7
	v_sub_f32_e32 v7, v30, v126
	v_add_f32_e32 v3, 0, v125
	v_mul_f32_e32 v7, 0x3fb8aa3b, v7
	v_add_f32_e32 v3, v124, v3
	v_exp_f32_e32 v24, v7
	v_sub_f32_e32 v7, v29, v126
	v_add_f32_e32 v3, v123, v3
	v_mul_f32_e32 v7, 0x3fb8aa3b, v7
	v_add_f32_e32 v3, v122, v3
	v_exp_f32_e32 v25, v7
	v_sub_f32_e32 v7, v28, v126
	v_add_f32_e32 v3, v121, v3
	v_mul_f32_e32 v7, 0x3fb8aa3b, v7
	v_add_f32_e32 v3, v43, v3
	v_exp_f32_e32 v26, v7
	v_sub_f32_e32 v7, v23, v126
	v_add_f32_e32 v3, v42, v3
	v_mul_f32_e32 v7, 0x3fb8aa3b, v7
	v_add_f32_e32 v3, v40, v3
	v_exp_f32_e32 v23, v7
	v_sub_f32_e32 v7, v22, v126
	v_add_f32_e32 v3, v27, v3
	v_mul_f32_e32 v7, 0x3fb8aa3b, v7
	v_add_f32_e32 v3, v127, v3
	v_exp_f32_e32 v135, v7
	v_sub_f32_e32 v7, v21, v126
	v_add_f32_e32 v3, v128, v3
	v_mul_f32_e32 v7, 0x3fb8aa3b, v7
	v_add_f32_e32 v3, v129, v3
	v_exp_f32_e32 v136, v7
	v_sub_f32_e32 v7, v17, v126
	v_add_f32_e32 v3, v130, v3
	v_mul_f32_e32 v7, 0x3fb8aa3b, v7
	v_add_f32_e32 v3, v131, v3
	v_exp_f32_e32 v17, v7
	v_sub_f32_e32 v7, v16, v126
	v_add_f32_e32 v3, v132, v3
	v_mul_f32_e32 v7, 0x3fb8aa3b, v7
	v_add_f32_e32 v3, v134, v3
	v_exp_f32_e32 v16, v7
	v_sub_f32_e32 v7, v15, v126
	v_add_f32_e32 v3, v18, v3
	v_mul_f32_e32 v7, 0x3fb8aa3b, v7
	v_add_f32_e32 v3, v19, v3
	v_exp_f32_e32 v15, v7
	v_sub_f32_e32 v7, v14, v126
	v_add_f32_e32 v3, v24, v3
	v_mul_f32_e32 v7, 0x3fb8aa3b, v7
	v_add_f32_e32 v3, v25, v3
	v_exp_f32_e32 v14, v7
	v_sub_f32_e32 v7, v13, v126
	v_add_f32_e32 v3, v26, v3
	v_mul_f32_e32 v7, 0x3fb8aa3b, v7
	v_add_f32_e32 v3, v23, v3
	v_exp_f32_e32 v13, v7
	v_sub_f32_e32 v7, v12, v126
	v_add_f32_e32 v3, v135, v3
	v_mul_f32_e32 v7, 0x3fb8aa3b, v7
	v_add_f32_e32 v3, v136, v3
	v_exp_f32_e32 v12, v7
	v_sub_f32_e32 v7, v11, v126
	v_add_f32_e32 v3, v17, v3
	v_mul_f32_e32 v7, 0x3fb8aa3b, v7
	v_add_f32_e32 v3, v16, v3
	v_exp_f32_e32 v11, v7
	v_sub_f32_e32 v7, v10, v126
	v_add_f32_e32 v3, v15, v3
	v_mul_f32_e32 v7, 0x3fb8aa3b, v7
	v_add_f32_e32 v3, v14, v3
	v_exp_f32_e32 v10, v7
	v_add_f32_e32 v3, v13, v3
	v_add_f32_e32 v3, v12, v3
	v_add_f32_e32 v3, v11, v3
	v_add_f32_e32 v7, v10, v3
	v_sub_f32_e32 v3, v9, v126
	v_mul_f32_e32 v3, 0x3fb8aa3b, v3
	v_exp_f32_e32 v3, v3
	v_sub_f32_e32 v6, v6, v126
	v_mul_f32_e32 v6, 0x3fb8aa3b, v6
	v_sub_f32_e32 v5, v5, v126
	v_add_f32_e32 v9, v3, v7
	v_sub_f32_e32 v7, v8, v126
	v_mul_f32_e32 v7, 0x3fb8aa3b, v7
	v_exp_f32_e32 v7, v7
	v_exp_f32_e32 v6, v6
	v_mul_f32_e32 v5, 0x3fb8aa3b, v5
	v_sub_f32_e32 v4, v4, v126
	v_exp_f32_e32 v5, v5
	v_mul_f32_e32 v4, 0x3fb8aa3b, v4
	v_sub_f32_e32 v1, v1, v126
	v_exp_f32_e32 v4, v4
	v_mul_f32_e32 v1, 0x3fb8aa3b, v1
	v_sub_f32_e32 v2, v2, v126
	v_add_f32_e32 v8, v7, v9
	v_exp_f32_e32 v1, v1
	v_mul_f32_e32 v2, 0x3fb8aa3b, v2
	v_add_f32_e32 v8, v6, v8
	v_exp_f32_e32 v2, v2
	v_add_f32_e32 v8, v5, v8
	v_add_f32_e32 v8, v4, v8
	v_sub_f32_e32 v0, v0, v126
	v_add_f32_e32 v8, v1, v8
	v_mul_f32_e32 v0, 0x3fb8aa3b, v0
	v_add_f32_e32 v9, v2, v8
	v_exp_f32_e32 v8, v0
	v_add_u32_e32 v22, 0x9000, v119
	v_add_u32_e32 v21, 0xb000, v119
	v_cvt_pk_bf16_f32 v28, v125, v124
	v_add_f32_e32 v0, v8, v9
	ds_bpermute_b32 v9, v104, v0
	v_cvt_pk_bf16_f32 v29, v123, v122
	v_cvt_pk_bf16_f32 v30, v121, v43
	v_cvt_pk_bf16_f32 v31, v42, v40
	ds_read2_b64 v[32:35], v22 offset1:4
	s_waitcnt lgkmcnt(1)
	v_add_f32_e32 v0, v0, v9
	ds_bpermute_b32 v9, v105, v0
	ds_read2_b64 v[36:39], v21 offset0:32 offset1:36
	s_waitcnt lgkmcnt(2)
	v_mfma_f32_16x16x32_bf16 v[32:35], v[32:35], v[28:31], 0
	s_waitcnt lgkmcnt(1)
	v_add_f32_e32 v0, v0, v9
	v_sub_f32_e32 v9, v20, v126
	v_mul_f32_e32 v9, 0x3fb8aa3b, v9
	v_exp_f32_e32 v9, v9
	v_add_u32_e32 v20, 0xd000, v119
	ds_read2_b64 v[40:43], v20 offset0:64 offset1:68
	s_waitcnt lgkmcnt(1)
; #define LAS __attribute__((address_space(3)))
; __device__ __forceinline__ unsigned cvt_pk_bf16(float lo, float hi) { unsigned r; asm("v_cvt_pk_bf16_f32 %0, %1, %2" : "=v"(r) : "v"(lo), "v"(hi)); return r; }
; __device__ __forceinline__ void ldbf8(const bf16_t* p, f32x4& a, f32x4& b) { const u32x4 w = *(const u32x4*)p; a = (f32x4){bf_lo(w.x), bf_hi(w.x), bf_lo(w.y), bf_hi(w.y)}; b = (f32x4){bf_lo(w.z), bf_hi(w.z), bf_lo(w.w), bf_hi(w.w)}; }
; __device__ __forceinline__ void attn_prompt_item(kp_t kp, LAS unsigned char* lds, int l, int item, const bf16_t* Z, float* YM, int tid, int lane, int wave) {
;     ...
;             for (int ks = 0; ks < 2; ++ks) ldbf8(qp + (h4 + 1) * 64 + ks * 32, qa[ks], qb[ks]);
;     ...
;         const float inv = 1.0f / (sum + __expf(sink - m));
;         f32x4 oc[4];
; #pragma unroll
;         for (int dt = 0; dt < 4; ++dt) oc[dt] = (f32x4){0.f, 0.f, 0.f, 0.f};
; #pragma unroll
;         for (int s5 = 0; s5 < 5; ++s5) {
;             u32x4 w; w.x = cvt_pk_bf16(sc[2 * s5][0], sc[2 * s5][1]); w.y = cvt_pk_bf16(sc[2 * s5][2], sc[2 * s5][3]); w.z = cvt_pk_bf16(sc[2 * s5 + 1][0], sc[2 * s5 + 1][1]); w.w = cvt_pk_bf16(sc[2 * s5 + 1][2], sc[2 * s5 + 1][3]);
;             const bf16x8 pb = __builtin_bit_cast(bf16x8, w);
; #pragma unroll
;             for (int dt = 0; dt < 4; ++dt) { const LAS unsigned char* vr = Vt + (dt * 16 + fr) * 528 + (kbase + 32 * s5 + 4 * fq) * 2;
;                 const u32x2 lo = *(const LAS u32x2*)vr, hi = *(const LAS u32x2*)(vr + 32);
;                 u32x4 av; av.x = lo.x; av.y = lo.y; av.z = hi.x; av.w = hi.y;
;                 oc[dt] = __builtin_amdgcn_mfma_f32_16x16x32_bf16(__builtin_bit_cast(bf16x8, av), pb, oc[dt], 0, 0, 0); } }
;         float* op = YM + tq * DM + 1024 + h * 64 + 4 * fq;
; #pragma unroll
;         for (int dt = 0; dt < 4; ++dt) *(f32x4*)(op + 16 * dt) = oc[dt] * inv;
	v_mfma_f32_16x16x32_bf16 v[36:39], v[36:39], v[28:31], 0
	v_add_f32_e32 v0, v9, v0
	v_add_u32_e32 v9, 0x9000, v120
	ds_read2_b64 v[122:125], v9 offset1:4
	s_waitcnt lgkmcnt(1)
	v_mfma_f32_16x16x32_bf16 v[40:43], v[40:43], v[28:31], 0
	v_cvt_pk_bf16_f32 v16, v17, v16
	v_cvt_pk_bf16_f32 v17, v15, v14
	s_waitcnt lgkmcnt(0)
	v_mfma_f32_16x16x32_bf16 v[28:31], v[122:125], v[28:31], 0
	v_cvt_pk_bf16_f32 v122, v27, v127
	v_cvt_pk_bf16_f32 v123, v128, v129
	ds_read2_b64 v[126:129], v22 offset0:8 offset1:12
	v_cvt_pk_bf16_f32 v124, v130, v131
	v_cvt_pk_bf16_f32 v125, v132, v134
	s_waitcnt lgkmcnt(0)
	v_mfma_f32_16x16x32_bf16 v[32:35], v[126:129], v[122:125], v[32:35]
	ds_read2_b64 v[126:129], v21 offset0:40 offset1:44
	s_waitcnt lgkmcnt(0)
	v_mfma_f32_16x16x32_bf16 v[36:39], v[126:129], v[122:125], v[36:39]
	ds_read2_b64 v[126:129], v20 offset0:72 offset1:76
	s_waitcnt lgkmcnt(0)
	v_mfma_f32_16x16x32_bf16 v[40:43], v[126:129], v[122:125], v[40:43]
	ds_read2_b64 v[126:129], v9 offset0:8 offset1:12
	s_waitcnt lgkmcnt(0)
	v_mfma_f32_16x16x32_bf16 v[28:31], v[126:129], v[122:125], v[28:31]
	v_cvt_pk_bf16_f32 v123, v24, v25
	v_cvt_pk_bf16_f32 v124, v26, v23
	ds_read2_b64 v[24:27], v22 offset0:16 offset1:20
	v_cvt_pk_bf16_f32 v122, v18, v19
	v_cvt_pk_bf16_f32 v18, v13, v12
	v_cvt_pk_bf16_f32 v19, v11, v10
	ds_read2_b64 v[10:13], v22 offset0:24 offset1:28
	v_cvt_pk_bf16_f32 v125, v135, v136
	s_waitcnt lgkmcnt(1)
	v_mfma_f32_16x16x32_bf16 v[24:27], v[24:27], v[122:125], v[32:35]
	s_nop 2
	ds_read2_b64 v[32:35], v21 offset0:48 offset1:52
	s_waitcnt lgkmcnt(1)
	v_mfma_f32_16x16x32_bf16 v[10:13], v[10:13], v[16:19], v[24:27]
	s_nop 2
	ds_read2_b64 v[24:27], v21 offset0:56 offset1:60
	s_waitcnt lgkmcnt(1)
	v_mfma_f32_16x16x32_bf16 v[32:35], v[32:35], v[122:125], v[36:39]
	s_nop 2
	ds_read2_b64 v[36:39], v20 offset0:80 offset1:84
	s_waitcnt lgkmcnt(1)
	v_mfma_f32_16x16x32_bf16 v[24:27], v[24:27], v[16:19], v[32:35]
	s_nop 2
	ds_read2_b64 v[32:35], v20 offset0:88 offset1:92
	s_waitcnt lgkmcnt(1)
	v_mfma_f32_16x16x32_bf16 v[36:39], v[36:39], v[122:125], v[40:43]
	s_nop 2
	ds_read2_b64 v[40:43], v9 offset0:16 offset1:20
	s_waitcnt lgkmcnt(1)
	v_mfma_f32_16x16x32_bf16 v[32:35], v[32:35], v[16:19], v[36:39]
	s_nop 2
	ds_read2_b64 v[36:39], v9 offset0:24 offset1:28
	s_waitcnt lgkmcnt(1)
	v_mfma_f32_16x16x32_bf16 v[28:31], v[40:43], v[122:125], v[28:31]
	s_waitcnt lgkmcnt(0)
	v_mfma_f32_16x16x32_bf16 v[14:17], v[36:39], v[16:19], v[28:31]
	v_cvt_pk_bf16_f32 v28, v3, v7
	v_cvt_pk_bf16_f32 v29, v6, v5
	v_cvt_pk_bf16_f32 v30, v4, v1
	v_cvt_pk_bf16_f32 v31, v2, v8
	ds_read2_b64 v[2:5], v22 offset0:32 offset1:36
	ds_read2_b64 v[6:9], v9 offset0:32 offset1:36
	v_div_scale_f32 v1, s[0:1], v0, v0, 1.0
	s_waitcnt lgkmcnt(1)
	s_nop 1
	v_mfma_f32_16x16x32_bf16 v[2:5], v[2:5], v[28:31], v[10:13]
	s_nop 2
	ds_read2_b64 v[10:13], v21 offset0:64 offset1:68
	ds_read2_b64 v[18:21], v20 offset0:96 offset1:100
	s_mov_b64 s[0:1], 0x100
	s_waitcnt lgkmcnt(2)
	v_mfma_f32_16x16x32_bf16 v[6:9], v[6:9], v[28:31], v[14:17]
	s_nop 2
	v_rcp_f32_e32 v14, v1
	s_waitcnt lgkmcnt(1)
	v_mfma_f32_16x16x32_bf16 v[10:13], v[10:13], v[28:31], v[24:27]
	v_fma_f32 v15, -v1, v14, 1.0
	v_fmac_f32_e32 v14, v15, v14
	v_div_scale_f32 v15, vcc, 1.0, v0, 1.0
	v_mul_f32_e32 v16, v15, v14
	v_fma_f32 v17, -v1, v16, v15
	v_fmac_f32_e32 v16, v17, v14
	v_fma_f32 v1, -v1, v16, v15
	s_waitcnt lgkmcnt(0)
	v_mfma_f32_16x16x32_bf16 v[18:21], v[18:21], v[28:31], v[32:35]
	v_div_fmas_f32 v1, v1, v14, v16
	v_div_fixup_f32 v14, v1, v0, 1.0
	v_pk_mul_f32 v[4:5], v[14:15], v[4:5] op_sel_hi:[0,1]
	v_pk_mul_f32 v[2:3], v[14:15], v[2:3] op_sel_hi:[0,1]
	s_waitcnt vmcnt(0)
	v_lshlrev_b32_e32 v72, 16, v216
	v_and_b32_e32 v74, 0xffff0000, v216
	v_lshlrev_b32_e32 v76, 16, v217
	v_and_b32_e32 v78, 0xffff0000, v217
	v_lshlrev_b32_e32 v80, 16, v218
	v_and_b32_e32 v82, 0xffff0000, v218
	v_lshlrev_b32_e32 v84, 16, v219
	v_and_b32_e32 v86, 0xffff0000, v219
	v_lshlrev_b32_e32 v73, 16, v220
	v_and_b32_e32 v75, 0xffff0000, v220
	v_lshlrev_b32_e32 v77, 16, v221
	v_and_b32_e32 v79, 0xffff0000, v221
	v_lshlrev_b32_e32 v81, 16, v222
	v_and_b32_e32 v83, 0xffff0000, v222
	v_lshlrev_b32_e32 v85, 16, v223
	v_and_b32_e32 v87, 0xffff0000, v223
	global_store_dwordx4 v[102:103], v[2:5], off offset:-128
	v_pk_mul_f32 v[0:1], v[14:15], v[10:11] op_sel_hi:[0,1]
	s_nop 0
	v_pk_mul_f32 v[2:3], v[14:15], v[12:13] op_sel_hi:[0,1]
	global_store_dwordx4 v[102:103], v[0:3], off offset:-64
	s_nop 1
	v_pk_mul_f32 v[2:3], v[14:15], v[20:21] op_sel_hi:[0,1]
	v_pk_mul_f32 v[0:1], v[14:15], v[18:19] op_sel_hi:[0,1]
	global_store_dwordx4 v[102:103], v[0:3], off
	s_nop 1
	v_pk_mul_f32 v[2:3], v[14:15], v[8:9] op_sel_hi:[0,1]
	v_pk_mul_f32 v[0:1], v[14:15], v[6:7] op_sel_hi:[0,1]
	global_store_dwordx4 v[102:103], v[0:3], off offset:64
	v_lshl_add_u64 v[102:103], v[102:103], 0, s[0:1]
	s_cbranch_scc0 .LBB0_88
; __device__ __forceinline__ unsigned cvt_pk_bf16(float lo, float hi) { unsigned r; asm("v_cvt_pk_bf16_f32 %0, %1, %2" : "=v"(r) : "v"(lo), "v"(hi)); return r; }
; __device__ __forceinline__ void ldbf8(const bf16_t* p, f32x4& a, f32x4& b) { const u32x4 w = *(const u32x4*)p; a = (f32x4){bf_lo(w.x), bf_hi(w.x), bf_lo(w.y), bf_hi(w.y)}; b = (f32x4){bf_lo(w.z), bf_hi(w.z), bf_lo(w.w), bf_hi(w.w)}; }
; __device__ __forceinline__ void attn_prompt_item(kp_t kp, LAS unsigned char* lds, int l, int item, const bf16_t* Z, float* YM, int tid, int lane, int wave) {
;     ...
;         { float ss = 0.f;
; #pragma unroll
;           for (int ks = 0; ks < 2; ++ks) ss += (qa[ks][0] * qa[ks][0] + qa[ks][1] * qa[ks][1]) + (qa[ks][2] * qa[ks][2] + qa[ks][3] * qa[ks][3]) + (qb[ks][0] * qb[ks][0] + qb[ks][1] * qb[ks][1]) + (qb[ks][2] * qb[ks][2] + qb[ks][3] * qb[ks][3]);
;           ss += __shfl_xor(ss, 16); ss += __shfl_xor(ss, 32);
;           const float rs = 0.125f / sqrtf(ss * (1.0f / 64.0f) + EPS);
; #pragma unroll
;           for (int ks = 0; ks < 2; ++ks) { const f32x4 g0 = *(const f32x4*)(gq + ks * 32 + fq * 8), g1 = *(const f32x4*)(gq + ks * 32 + fq * 8 + 4);
;               u32x4 w; w.x = cvt_pk_bf16(qa[ks][0] * rs * g0[0], qa[ks][1] * rs * g0[1]); w.y = cvt_pk_bf16(qa[ks][2] * rs * g0[2], qa[ks][3] * rs * g0[3]);
;               w.z = cvt_pk_bf16(qb[ks][0] * rs * g1[0], qb[ks][1] * rs * g1[1]); w.w = cvt_pk_bf16(qb[ks][2] * rs * g1[2], qb[ks][3] * rs * g1[3]);
;               qf[ks] = __builtin_bit_cast(bf16x8, w); } }
;         if (h4 < 3) {
; #pragma unroll
;             for (int ks = 0; ks < 2; ++ks) ldbf8(qp + (h4 + 1) * 64 + ks * 32, qa[ks], qb[ks]);
.LBB0_84:
	s_cmpk_eq_i32 s8, 0x180
	s_cbranch_scc1 .Lattn_no_next_q
	v_lshl_add_u64 v[224:225], v[100:101], 0, s[8:9]
	s_nop 0
	v_add_co_u32_e32 v224, vcc, 0xb800000, v224
	s_nop 1
	v_addc_co_u32_e32 v225, vcc, 0, v225, vcc
	global_load_dwordx4 v[216:219], v[224:225], off offset:2176
	global_load_dwordx4 v[220:223], v[224:225], off offset:2240
.Lattn_no_next_q:
	v_pk_mul_f32 v[0:1], v[74:75], v[74:75]
	v_pk_mul_f32 v[2:3], v[78:79], v[78:79]
	v_pk_fma_f32 v[0:1], v[72:73], v[72:73], v[0:1]
	v_pk_fma_f32 v[2:3], v[76:77], v[76:77], v[2:3]
	s_mov_b32 s0, 0xf800000
	v_pk_add_f32 v[0:1], v[0:1], v[2:3]
	v_pk_mul_f32 v[2:3], v[82:83], v[82:83]
	s_mov_b32 s3, 0x3e000000
	v_pk_fma_f32 v[2:3], v[80:81], v[80:81], v[2:3]
	s_cmpk_eq_i32 s8, 0x180
	v_pk_add_f32 v[0:1], v[2:3], v[0:1]
	v_pk_mul_f32 v[2:3], v[86:87], v[86:87]
	s_nop 0
	v_pk_fma_f32 v[2:3], v[84:85], v[84:85], v[2:3]
	s_nop 0
	v_pk_add_f32 v[0:1], v[2:3], v[0:1]
	s_nop 0
	v_add_f32_e32 v0, v0, v1
	ds_bpermute_b32 v1, v104, v0
	s_waitcnt lgkmcnt(0)
	v_add_f32_e32 v0, v0, v1
	ds_bpermute_b32 v1, v105, v0
	s_waitcnt lgkmcnt(0)
	v_add_f32_e32 v0, v0, v1
	v_fmamk_f32 v0, v0, 0x3c800000, v179
	v_cmp_gt_f32_e64 s[0:1], s0, v0
	v_mul_f32_e32 v1, 0x4f800000, v0
	s_nop 0
	v_cndmask_b32_e64 v0, v0, v1, s[0:1]
	v_sqrt_f32_e32 v1, v0
	s_nop 0
	v_add_u32_e32 v2, -1, v1
	v_fma_f32 v3, -v2, v1, v0
	v_cmp_ge_f32_e32 vcc, 0, v3
	v_add_u32_e32 v3, 1, v1
	s_nop 0
	v_cndmask_b32_e32 v2, v1, v2, vcc
	v_fma_f32 v1, -v3, v1, v0
	v_cmp_lt_f32_e32 vcc, 0, v1
	s_nop 1
	v_cndmask_b32_e32 v1, v2, v3, vcc
	v_mul_f32_e32 v2, 0x37800000, v1
	v_cndmask_b32_e64 v1, v1, v2, s[0:1]
	v_cmp_class_f32_e32 vcc, v0, v180
	s_nop 1
	v_cndmask_b32_e32 v0, v1, v0, vcc
	v_div_scale_f32 v1, s[0:1], v0, v0, s3
	v_rcp_f32_e32 v2, v1
	s_nop 0
	v_fma_f32 v3, -v1, v2, 1.0
	v_fmac_f32_e32 v2, v3, v2
	v_div_scale_f32 v3, vcc, s3, v0, s3
	v_mul_f32_e32 v4, v3, v2
	v_fma_f32 v5, -v1, v4, v3
	v_fmac_f32_e32 v4, v5, v2
	v_fma_f32 v1, -v1, v4, v3
	v_div_fmas_f32 v1, v1, v2, v4
	v_div_fixup_f32 v8, v1, v0, s3
	v_mul_f32_e32 v0, v72, v8
	v_mul_f32_e32 v1, v74, v8
	v_mul_f32_e32 v6, v78, v8
	v_mul_f32_e32 v9, v73, v8
	v_mul_f32_e32 v0, v200, v0
	v_mul_f32_e32 v1, v201, v1
	v_cvt_pk_bf16_f32 v0, v0, v1
	v_mul_f32_e32 v1, v76, v8
	v_mul_f32_e32 v1, v202, v1
	v_mul_f32_e32 v6, v203, v6
	v_cvt_pk_bf16_f32 v1, v1, v6
	v_mul_f32_e32 v6, v80, v8
	v_mul_f32_e32 v2, v204, v6
	v_mul_f32_e32 v6, v82, v8
	v_mul_f32_e32 v3, v205, v6
	v_cvt_pk_bf16_f32 v2, v2, v3
	v_mul_f32_e32 v3, v84, v8
	v_mul_f32_e32 v3, v206, v3
	v_mul_f32_e32 v4, v86, v8
	v_mul_f32_e32 v4, v207, v4
	v_cvt_pk_bf16_f32 v3, v3, v4
	v_mul_f32_e32 v9, v208, v9
	v_mul_f32_e32 v10, v75, v8
	v_mul_f32_e32 v10, v209, v10
	v_cvt_pk_bf16_f32 v20, v9, v10
	v_mul_f32_e32 v9, v77, v8
	v_mul_f32_e32 v9, v210, v9
	v_mul_f32_e32 v10, v79, v8
	v_mul_f32_e32 v10, v211, v10
	v_cvt_pk_bf16_f32 v21, v9, v10
	v_mul_f32_e32 v9, v81, v8
	v_mul_f32_e32 v4, v212, v9
	v_mul_f32_e32 v9, v83, v8
	v_mul_f32_e32 v5, v213, v9
	v_cvt_pk_bf16_f32 v22, v4, v5
	v_mul_f32_e32 v4, v85, v8
	v_mul_f32_e32 v5, v87, v8
	v_mul_f32_e32 v4, v214, v4
	v_mul_f32_e32 v5, v215, v5
	v_cvt_pk_bf16_f32 v23, v4, v5
	s_cbranch_scc1 .LBB0_86

; __device__ __forceinline__ unsigned cvt_pk_bf16(float lo, float hi) { unsigned r; asm("v_cvt_pk_bf16_f32 %0, %1, %2" : "=v"(r) : "v"(lo), "v"(hi)); return r; }
; __device__ __forceinline__ void ssm_lane_math(const SsmRaw& r, float& lr, float& li, float (&bre)[16], float (&bim)[16]) {
;     const float Are = r.Are, Aim = r.Aim;
;     const float dt = expf(r.ldt);
;     const float er = expf(Are * dt);
;     const float ang = Aim * dt;
;     lr = er * cosf(ang); li = er * sinf(ang);
;     const float den = Are * Are + Aim * Aim, nr = lr - 1.0f, ni = li;
;     const float cr = (nr * Are + ni * Aim) / den, ci = (ni * Are - nr * Aim) / den;
; #pragma unroll
;     for (int q = 0; q < 4; ++q)
; #pragma unroll
;         for (int e = 0; e < 4; ++e) { bre[4 * q + e] = cr * r.br[q][e] - ci * r.bi[q][e]; bim[4 * q + e] = cr * r.bi[q][e] + ci * r.br[q][e]; }
; template <bool SAMPLE>
; __device__ __forceinline__ void ssm_item(kp_t kp, LAS unsigned char* lds, int l, int item, const bf16_t* Z, float* YM, int tid, int lane, int wave) {
;     ...
;       for (int ks = 0; ks < 4; ++ks) { const f32x4 cr = craw[ks], ci = ciraw[ks];
;           u32x4 w; w.x = cvt_pk_bf16(cr[0], -ci[0]); w.y = cvt_pk_bf16(cr[1], -ci[1]); w.z = cvt_pk_bf16(cr[2], -ci[2]); w.w = cvt_pk_bf16(cr[3], -ci[3]);
;           cf[ks] = __builtin_bit_cast(bf16x8, w); } }
.LBB0_99:
	s_or_b64 exec, exec, s[0:1]
	v_mul_f32_e32 v0, v72, v0
	v_mul_f32_e32 v71, 0x3fb8aa3b, v0
	s_mov_b32 s0, 0x3fb8aa3b
	v_fma_f32 v74, v0, s0, -v71
	v_rndne_f32_e32 v77, v71
	v_fmac_f32_e32 v74, 0x32a5705f, v0
	v_sub_f32_e32 v71, v71, v77
	v_add_f32_e32 v71, v71, v74
	v_cvt_i32_f32_e32 v74, v77
	v_exp_f32_e32 v71, v71
	s_mov_b32 s0, 0xc2ce8ed0
	v_cmp_ngt_f32_e32 vcc, s0, v0
	s_mov_b32 s0, 0x42b17218
	v_ldexp_f32 v71, v71, v74
	v_cndmask_b32_e32 v71, 0, v71, vcc
	v_cmp_nlt_f32_e32 vcc, s0, v0
	v_mul_f32_e32 v0, v68, v68
	s_brev_b32 s0, 1
	v_cndmask_b32_e32 v77, v192, v71, vcc
	v_fmamk_f32 v71, v0, 0xb94c1982, v181
	v_fmaak_f32 v71, v0, v71, 0xbe2aaa9d
	v_mul_f32_e32 v71, v0, v71
	v_fmac_f32_e32 v68, v68, v71
	v_fmamk_f32 v71, v0, 0x37d75334, v182
	v_fmaak_f32 v71, v0, v71, 0x3d2aabf7
	v_fmaak_f32 v71, v0, v71, 0xbf000004
	v_fma_f32 v0, v0, v71, 1.0
	v_and_b32_e32 v71, 1, v1
	v_cmp_eq_u32_e32 vcc, 0, v71
	v_mul_f32_e32 v71, v76, v76
	v_fmamk_f32 v74, v71, 0xb94c1982, v181
	v_fmaak_f32 v74, v71, v74, 0xbe2aaa9d
	v_mul_f32_e32 v74, v71, v74
	v_fmac_f32_e32 v76, v76, v74
	v_fmamk_f32 v74, v71, 0x37d75334, v182
	v_cndmask_b32_e64 v0, -v68, v0, vcc
	v_lshlrev_b32_e32 v1, 30, v1
	v_fmaak_f32 v74, v71, v74, 0x3d2aabf7
	v_bitop3_b32 v0, v1, v0, s0 bitop3:0x6c
	s_movk_i32 s0, 0x1f8
	v_fmaak_f32 v74, v71, v74, 0xbf000004
	v_cmp_class_f32_e64 vcc, v69, s0
	v_readlane_b32 s0, v253, 48
	v_fma_f32 v71, v71, v74, 1.0
	v_and_b32_e32 v74, 1, v75
	s_and_b32 s4, s0, 63
	v_cmp_eq_u32_e64 s[0:1], 0, v74
	v_lshlrev_b32_e32 v74, 30, v75
	v_and_b32_e32 v74, 0x80000000, v74
	v_xor_b32_e32 v69, v70, v69
	v_cndmask_b32_e64 v71, v71, v76, s[0:1]
	v_xor_b32_e32 v69, v69, v74
	v_xor_b32_e32 v69, v69, v71
	v_cndmask_b32_e32 v78, v195, v0, vcc
	v_cndmask_b32_e32 v69, v195, v69, vcc
	v_mul_f32_e32 v71, v77, v69
	v_fma_f32 v70, v77, v78, -1.0
	v_mov_b32_e32 v76, v73
	v_mul_f32_e32 v68, v77, v78
	v_pk_mul_f32 v[74:75], v[72:73], v[72:73]
	v_pk_mul_f32 v[76:77], v[76:77], v[70:71] op_sel:[0,1] op_sel_hi:[0,0]
	v_pk_fma_f32 v[78:79], v[72:73], v[70:71], v[76:77] op_sel_hi:[0,1,1] neg_lo:[0,0,1] neg_hi:[0,0,1]
	v_pk_add_f32 v[74:75], v[74:75], v[74:75] op_sel:[0,1] op_sel_hi:[0,1]
	v_div_scale_f32 v69, s[0:1], v75, v75, v79
	v_rcp_f32_e32 v78, v69
	v_pk_fma_f32 v[72:73], v[72:73], v[70:71], v[76:77]
	s_waitcnt vmcnt(18)
	v_xor_b32_e32 v20, 0x80000000, v20
	v_cvt_pk_bf16_f32 v16, v16, v20
	v_fma_f32 v70, -v69, v78, 1.0
	v_fmac_f32_e32 v78, v70, v78
	v_div_scale_f32 v70, vcc, v79, v75, v79
	v_mul_f32_e32 v73, v70, v78
	v_fma_f32 v76, -v69, v73, v70
	v_fmac_f32_e32 v73, v76, v78
	v_fma_f32 v69, -v69, v73, v70
	v_div_scale_f32 v70, s[0:1], v74, v74, v72
	v_rcp_f32_e32 v76, v70
	v_div_fmas_f32 v69, v69, v78, v73
	v_div_fixup_f32 v75, v69, v75, v79
	v_xor_b32_e32 v20, 0x80000000, v21
	v_fma_f32 v69, -v70, v76, 1.0
	v_fmac_f32_e32 v76, v69, v76
	v_div_scale_f32 v69, vcc, v72, v74, v72
	v_mul_f32_e32 v73, v69, v76
	v_fma_f32 v77, -v70, v73, v69
	v_fmac_f32_e32 v73, v77, v76
	v_fma_f32 v69, -v70, v73, v69
	v_div_fmas_f32 v69, v69, v76, v73
	v_div_fixup_f32 v74, v69, v74, v72
	v_pk_mul_f32 v[76:77], v[64:65], v[74:75] op_sel:[0,1] op_sel_hi:[0,0]
	v_pk_fma_f32 v[72:73], v[60:61], v[74:75], v[76:77] neg_lo:[0,0,1] neg_hi:[0,0,1]
	v_pk_fma_f32 v[76:77], v[60:61], v[74:75], v[76:77] op_sel_hi:[0,1,1]
	v_mov_b32_e32 v73, v77
	v_pk_mul_f32 v[76:77], v[64:65], v[74:75] op_sel:[1,1] op_sel_hi:[1,0]
	v_mov_b32_e32 v70, v63
	v_pk_fma_f32 v[64:65], v[60:61], v[74:75], v[76:77] op_sel:[1,0,0] neg_lo:[0,0,1] neg_hi:[0,0,1]
	v_pk_fma_f32 v[60:61], v[60:61], v[74:75], v[76:77] op_sel:[1,0,0]
	v_pk_mul_f32 v[76:77], v[66:67], v[74:75] op_sel:[0,1] op_sel_hi:[0,0]
	v_mov_b32_e32 v65, v61
	v_pk_fma_f32 v[60:61], v[62:63], v[74:75], v[76:77] neg_lo:[0,0,1] neg_hi:[0,0,1]
	v_pk_fma_f32 v[76:77], v[62:63], v[74:75], v[76:77] op_sel_hi:[0,1,1]
	v_mov_b32_e32 v62, v67
	v_pk_mul_f32 v[66:67], v[62:63], v[74:75] op_sel:[0,1] op_sel_hi:[0,0]
	v_mov_b32_e32 v61, v77
	v_pk_fma_f32 v[62:63], v[70:71], v[74:75], v[66:67] op_sel_hi:[0,1,1] neg_lo:[0,0,1] neg_hi:[0,0,1]
	v_pk_fma_f32 v[66:67], v[70:71], v[74:75], v[66:67] op_sel_hi:[0,1,1]
	v_pk_mul_f32 v[76:77], v[56:57], v[74:75] op_sel:[0,1] op_sel_hi:[0,0]
	v_mov_b32_e32 v63, v67
	v_pk_fma_f32 v[66:67], v[52:53], v[74:75], v[76:77] neg_lo:[0,0,1] neg_hi:[0,0,1]
	v_pk_fma_f32 v[76:77], v[52:53], v[74:75], v[76:77] op_sel_hi:[0,1,1]
	v_mov_b32_e32 v52, v57
	v_pk_mul_f32 v[56:57], v[52:53], v[74:75] op_sel:[0,1] op_sel_hi:[0,0]
	v_mov_b32_e32 v70, v53
	v_mov_b32_e32 v67, v77
	v_pk_fma_f32 v[52:53], v[70:71], v[74:75], v[56:57] op_sel_hi:[0,1,1] neg_lo:[0,0,1] neg_hi:[0,0,1]
	v_pk_fma_f32 v[56:57], v[70:71], v[74:75], v[56:57] op_sel_hi:[0,1,1]
	v_pk_mul_f32 v[76:77], v[58:59], v[74:75] op_sel:[0,1] op_sel_hi:[0,0]
	v_mov_b32_e32 v53, v57
	v_pk_fma_f32 v[56:57], v[54:55], v[74:75], v[76:77] neg_lo:[0,0,1] neg_hi:[0,0,1]
	v_pk_fma_f32 v[76:77], v[54:55], v[74:75], v[76:77] op_sel_hi:[0,1,1]
	v_mov_b32_e32 v54, v59
	v_pk_mul_f32 v[58:59], v[54:55], v[74:75] op_sel:[0,1] op_sel_hi:[0,0]
	v_mov_b32_e32 v70, v55
	v_mov_b32_e32 v57, v77
	v_pk_fma_f32 v[54:55], v[70:71], v[74:75], v[58:59] op_sel_hi:[0,1,1] neg_lo:[0,0,1] neg_hi:[0,0,1]
	v_pk_fma_f32 v[58:59], v[70:71], v[74:75], v[58:59] op_sel_hi:[0,1,1]
	v_pk_mul_f32 v[76:77], v[48:49], v[74:75] op_sel:[0,1] op_sel_hi:[0,0]
	v_mov_b32_e32 v55, v59
	v_pk_fma_f32 v[58:59], v[44:45], v[74:75], v[76:77] neg_lo:[0,0,1] neg_hi:[0,0,1]
	v_pk_fma_f32 v[76:77], v[44:45], v[74:75], v[76:77] op_sel_hi:[0,1,1]
	v_mov_b32_e32 v44, v49
	v_pk_mul_f32 v[48:49], v[44:45], v[74:75] op_sel:[0,1] op_sel_hi:[0,0]
	v_mov_b32_e32 v70, v45
; __device__ __forceinline__ unsigned cvt_pk_bf16(float lo, float hi) { unsigned r; asm("v_cvt_pk_bf16_f32 %0, %1, %2" : "=v"(r) : "v"(lo), "v"(hi)); return r; }
; template <bool SAMPLE>
; __device__ __forceinline__ void ssm_item(kp_t kp, LAS unsigned char* lds, int l, int item, const bf16_t* Z, float* YM, int tid, int lane, int wave) {
;     ...
;     f32x2 pw[16];
;     { float pr = lr, pi = li;
; #pragma unroll
;       for (int tt = 0; tt < 16; ++tt) { pw[tt] = (f32x2){pr, pi}; const float npr = pr * lr - pi * li; pi = pr * li + pi * lr; pr = npr; } }
;     const float l16r = pw[15].x, l16i = pw[15].y;
;     bf16x8 cf[4];
;     {
; #pragma unroll
;       for (int ks = 0; ks < 4; ++ks) { const f32x4 cr = craw[ks], ci = ciraw[ks];
;           u32x4 w; w.x = cvt_pk_bf16(cr[0], -ci[0]); w.y = cvt_pk_bf16(cr[1], -ci[1]); w.z = cvt_pk_bf16(cr[2], -ci[2]); w.w = cvt_pk_bf16(cr[3], -ci[3]);
;           cf[ks] = __builtin_bit_cast(bf16x8, w); } }
	v_mov_b32_e32 v59, v77
	v_pk_fma_f32 v[44:45], v[70:71], v[74:75], v[48:49] op_sel_hi:[0,1,1] neg_lo:[0,0,1] neg_hi:[0,0,1]
	v_pk_fma_f32 v[48:49], v[70:71], v[74:75], v[48:49] op_sel_hi:[0,1,1]
	v_pk_mul_f32 v[76:77], v[50:51], v[74:75] op_sel:[0,1] op_sel_hi:[0,0]
	v_mov_b32_e32 v45, v49
	v_pk_fma_f32 v[48:49], v[46:47], v[74:75], v[76:77] neg_lo:[0,0,1] neg_hi:[0,0,1]
	v_pk_fma_f32 v[76:77], v[46:47], v[74:75], v[76:77] op_sel_hi:[0,1,1]
	v_mov_b32_e32 v46, v51
	v_pk_mul_f32 v[50:51], v[46:47], v[74:75] op_sel:[0,1] op_sel_hi:[0,0]
	v_mov_b32_e32 v70, v47
	v_mov_b32_e32 v49, v77
	v_pk_fma_f32 v[46:47], v[70:71], v[74:75], v[50:51] op_sel_hi:[0,1,1] neg_lo:[0,0,1] neg_hi:[0,0,1]
	v_pk_fma_f32 v[50:51], v[70:71], v[74:75], v[50:51] op_sel_hi:[0,1,1]
	v_pk_mul_f32 v[76:77], v[40:41], v[74:75] op_sel:[0,1] op_sel_hi:[0,0]
	v_mov_b32_e32 v47, v51
	v_pk_fma_f32 v[50:51], v[36:37], v[74:75], v[76:77] neg_lo:[0,0,1] neg_hi:[0,0,1]
	v_pk_fma_f32 v[76:77], v[36:37], v[74:75], v[76:77] op_sel_hi:[0,1,1]
	v_mov_b32_e32 v36, v41
	v_pk_mul_f32 v[40:41], v[36:37], v[74:75] op_sel:[0,1] op_sel_hi:[0,0]
	v_mov_b32_e32 v70, v37
	v_mov_b32_e32 v51, v77
	v_pk_fma_f32 v[36:37], v[70:71], v[74:75], v[40:41] op_sel_hi:[0,1,1] neg_lo:[0,0,1] neg_hi:[0,0,1]
	v_pk_fma_f32 v[40:41], v[70:71], v[74:75], v[40:41] op_sel_hi:[0,1,1]
	v_pk_mul_f32 v[76:77], v[42:43], v[74:75] op_sel:[0,1] op_sel_hi:[0,0]
	v_mov_b32_e32 v37, v41
	v_pk_fma_f32 v[40:41], v[38:39], v[74:75], v[76:77] neg_lo:[0,0,1] neg_hi:[0,0,1]
	v_pk_fma_f32 v[76:77], v[38:39], v[74:75], v[76:77] op_sel_hi:[0,1,1]
	v_mov_b32_e32 v38, v43
	v_pk_mul_f32 v[42:43], v[38:39], v[74:75] op_sel:[0,1] op_sel_hi:[0,0]
	v_mov_b32_e32 v70, v39
	v_mov_b32_e32 v69, v71
	v_pk_fma_f32 v[38:39], v[70:71], v[74:75], v[42:43] op_sel_hi:[0,1,1] neg_lo:[0,0,1] neg_hi:[0,0,1]
	v_pk_fma_f32 v[42:43], v[70:71], v[74:75], v[42:43] op_sel_hi:[0,1,1]
	v_pk_mul_f32 v[74:75], v[68:69], v[68:69] op_sel:[1,1] op_sel_hi:[0,1]
	v_pk_fma_f32 v[112:113], v[68:69], v[68:69], v[74:75] op_sel_hi:[0,1,1] neg_lo:[0,0,1] neg_hi:[0,0,1]
	v_pk_fma_f32 v[114:115], v[68:69], v[68:69], v[74:75] op_sel_hi:[0,1,1]
	v_mov_b32_e32 v41, v77
	v_pk_mov_b32 v[76:77], v[114:115], v[112:113] op_sel:[1,0]
	v_mov_b32_e32 v74, v112
	v_mov_b32_e32 v75, v115
	v_pk_mul_f32 v[76:77], v[68:69], v[76:77] op_sel:[1,0]
	v_mov_b32_e32 v70, v71
	v_pk_fma_f32 v[116:117], v[68:69], v[74:75], v[76:77] op_sel_hi:[0,1,1] neg_lo:[0,0,1] neg_hi:[0,0,1]
	v_pk_fma_f32 v[118:119], v[68:69], v[74:75], v[76:77] op_sel_hi:[0,1,1]
	v_pk_mov_b32 v[78:79], v[118:119], v[116:117] op_sel:[1,0]
	v_mov_b32_e32 v76, v116
	v_mov_b32_e32 v77, v119
	v_pk_mul_f32 v[78:79], v[68:69], v[78:79] op_sel:[1,0]
	v_cvt_pk_bf16_f32 v17, v17, v20
	v_xor_b32_e32 v20, 0x80000000, v22
	v_pk_fma_f32 v[120:121], v[68:69], v[76:77], v[78:79] op_sel_hi:[0,1,1] neg_lo:[0,0,1] neg_hi:[0,0,1]
	v_pk_fma_f32 v[122:123], v[68:69], v[76:77], v[78:79] op_sel_hi:[0,1,1]
	v_pk_mov_b32 v[80:81], v[122:123], v[120:121] op_sel:[1,0]
	v_mov_b32_e32 v78, v120
	v_mov_b32_e32 v79, v123
	v_pk_mul_f32 v[80:81], v[68:69], v[80:81] op_sel:[1,0]
	v_readlane_b32 s25, v253, 52
	v_pk_fma_f32 v[124:125], v[68:69], v[78:79], v[80:81] op_sel_hi:[0,1,1] neg_lo:[0,0,1] neg_hi:[0,0,1]
	v_pk_fma_f32 v[126:127], v[68:69], v[78:79], v[80:81] op_sel_hi:[0,1,1]
	v_pk_mov_b32 v[82:83], v[126:127], v[124:125] op_sel:[1,0]
	v_mov_b32_e32 v80, v124
	v_mov_b32_e32 v81, v127
	v_pk_mul_f32 v[82:83], v[68:69], v[82:83] op_sel:[1,0]
	v_cvt_pk_bf16_f32 v18, v18, v20
	v_xor_b32_e32 v20, 0x80000000, v23
	v_pk_fma_f32 v[128:129], v[68:69], v[80:81], v[82:83] op_sel_hi:[0,1,1] neg_lo:[0,0,1] neg_hi:[0,0,1]
	v_pk_fma_f32 v[130:131], v[68:69], v[80:81], v[82:83] op_sel_hi:[0,1,1]
	v_pk_mov_b32 v[84:85], v[130:131], v[128:129] op_sel:[1,0]
	v_mov_b32_e32 v82, v128
	v_mov_b32_e32 v83, v131
	v_pk_mul_f32 v[84:85], v[70:71], v[84:85] op_sel_hi:[0,1]
	v_pk_fma_f32 v[138:139], v[68:69], v[82:83], v[84:85] op_sel_hi:[0,1,1] neg_lo:[0,0,1] neg_hi:[0,0,1]
	v_pk_fma_f32 v[140:141], v[68:69], v[82:83], v[84:85] op_sel_hi:[0,1,1]
	v_pk_mov_b32 v[86:87], v[140:141], v[138:139] op_sel:[1,0]
	v_mov_b32_e32 v84, v138
	v_mov_b32_e32 v85, v141
	v_pk_mul_f32 v[86:87], v[70:71], v[86:87] op_sel_hi:[0,1]
	v_pk_fma_f32 v[142:143], v[68:69], v[84:85], v[86:87] op_sel_hi:[0,1,1] neg_lo:[0,0,1] neg_hi:[0,0,1]
	v_pk_fma_f32 v[144:145], v[68:69], v[84:85], v[86:87] op_sel_hi:[0,1,1]
	v_pk_mov_b32 v[88:89], v[144:145], v[142:143] op_sel:[1,0]
	v_mov_b32_e32 v86, v142
	v_mov_b32_e32 v87, v145
	v_pk_mul_f32 v[88:89], v[70:71], v[88:89] op_sel_hi:[0,1]
	v_pk_fma_f32 v[146:147], v[68:69], v[86:87], v[88:89] op_sel_hi:[0,1,1] neg_lo:[0,0,1] neg_hi:[0,0,1]
	v_pk_fma_f32 v[160:161], v[68:69], v[86:87], v[88:89] op_sel_hi:[0,1,1]
	v_pk_mov_b32 v[90:91], v[160:161], v[146:147] op_sel:[1,0]
	v_mov_b32_e32 v88, v146
	v_mov_b32_e32 v89, v161
	v_pk_mul_f32 v[90:91], v[70:71], v[90:91] op_sel_hi:[0,1]
	v_pk_fma_f32 v[162:163], v[68:69], v[88:89], v[90:91] op_sel_hi:[0,1,1] neg_lo:[0,0,1] neg_hi:[0,0,1]
	v_pk_fma_f32 v[164:165], v[68:69], v[88:89], v[90:91] op_sel_hi:[0,1,1]
	v_pk_mov_b32 v[92:93], v[164:165], v[162:163] op_sel:[1,0]
	v_mov_b32_e32 v90, v162
	v_mov_b32_e32 v91, v165
	v_pk_mul_f32 v[92:93], v[70:71], v[92:93] op_sel_hi:[0,1]
	v_pk_fma_f32 v[166:167], v[68:69], v[90:91], v[92:93] op_sel_hi:[0,1,1] neg_lo:[0,0,1] neg_hi:[0,0,1]
	v_pk_fma_f32 v[168:169], v[68:69], v[90:91], v[92:93] op_sel_hi:[0,1,1]
	v_mov_b32_e32 v92, v166
	v_mov_b32_e32 v93, v169
	v_pk_mul_f32 v[94:95], v[70:71], v[92:93] op_sel_hi:[0,1]
	v_pk_mov_b32 v[96:97], v[168:169], v[166:167] op_sel:[1,0]
	s_lshl_b32 s0, s25, 9
; #define LAS __attribute__((address_space(3)))
; __device__ __forceinline__ f32x4 ldbf4(const bf16_t* p) { const u32x2 w = *(const u32x2*)p; return (f32x4){bf_lo(w.x), bf_hi(w.x), bf_lo(w.y), bf_hi(w.y)}; }
; template <bool SAMPLE>
; __device__ __forceinline__ void ssm_item(kp_t kp, LAS unsigned char* lds, int l, int item, const bf16_t* Z, float* YM, int tid, int lane, int wave) {
;     ...
;     LAS float* Ub = (LAS float*)lds; LAS f32x2* Eb = (LAS f32x2*)(lds + 16384); LAS unsigned char* Hb = lds + 20480; LAS float* Yb = (LAS float*)(lds + 55296);
;     float car = 0.f, cai = 0.f;
;     constexpr int NCH = SAMPLE ? 1 : 16;
;     for (int ch = 0; ch < NCH; ++ch) {
;         const size_t tok0 = row0 + ch * 128;
;         LAS float* U = Ub + (ch & 1) * 2048;
;         *(LAS f32x4*)(U + tid * 4) = ureg;
;         if (ch < NCH - 1) ureg = ldbf4(zsrc + (size_t)(ch + 1) * 128 * INW);
;         __syncthreads();
;         f32x2 hl[16]; f32x2 h = (f32x2){0.f, 0.f};
	v_pk_fma_f32 v[98:99], v[68:69], v[96:97], v[94:95] op_sel_hi:[0,1,1]
	v_pk_fma_f32 v[170:171], v[68:69], v[96:97], v[94:95] op_sel_hi:[0,1,1] neg_lo:[0,0,1] neg_hi:[0,0,1]
	v_pk_mov_b32 v[94:95], v[170:171], v[98:99] op_sel:[1,0]
	v_mov_b32_e32 v172, v98
	v_mov_b32_e32 v173, v171
	v_pk_mul_f32 v[96:97], v[70:71], v[94:95] op_sel_hi:[0,1]
	v_pk_fma_f32 v[98:99], v[68:69], v[172:173], v[96:97] op_sel_hi:[0,1,1]
	v_pk_fma_f32 v[174:175], v[68:69], v[172:173], v[96:97] op_sel_hi:[0,1,1] neg_lo:[0,0,1] neg_hi:[0,0,1]
	v_pk_mov_b32 v[96:97], v[174:175], v[98:99] op_sel:[1,0]
	v_mov_b32_e32 v176, v98
	v_mov_b32_e32 v177, v175
	v_pk_mul_f32 v[98:99], v[70:71], v[96:97] op_sel_hi:[0,1]
	v_pk_fma_f32 v[100:101], v[68:69], v[176:177], v[98:99] op_sel_hi:[0,1,1]
	v_pk_fma_f32 v[188:189], v[68:69], v[176:177], v[98:99] op_sel_hi:[0,1,1] neg_lo:[0,0,1] neg_hi:[0,0,1]
	v_pk_mov_b32 v[98:99], v[188:189], v[100:101] op_sel:[1,0]
	v_mov_b32_e32 v190, v100
	v_mov_b32_e32 v191, v189
	v_pk_mul_f32 v[100:101], v[70:71], v[98:99] op_sel_hi:[0,1]
	v_cvt_pk_bf16_f32 v19, v19, v20
	s_add_i32 s0, s0, 0
	v_lshlrev_b32_e32 v20, 3, v110
	v_pk_fma_f32 v[102:103], v[68:69], v[190:191], v[100:101] op_sel_hi:[0,1,1]
	v_pk_fma_f32 v[218:219], v[68:69], v[190:191], v[100:101] op_sel_hi:[0,1,1] neg_lo:[0,0,1] neg_hi:[0,0,1]
	v_add_u32_e32 v217, s0, v20
	s_lshl_b32 s0, s25, 4
	v_pk_mov_b32 v[100:101], v[218:219], v[102:103] op_sel:[1,0]
	v_add_u32_e32 v218, 0, v20
	s_mov_b32 s84, 0xb800
	v_or_b32_e32 v20, s0, v136
	s_movk_i32 s1, 0x110
	v_mul_lo_u32 v20, v20, s1
	s_lshl_b32 s21, s4, 5
	s_lshl_b32 s20, s4, 6
	s_lshl_b32 s24, s25, 10
	v_add_u32_e32 v140, 0, v20
	v_or_b32_e32 v20, s0, v111
	v_readlane_b32 s0, v253, 51
	s_cmp_lt_u32 s0, 64
	s_cselect_b64 s[0:1], -1, 0
	s_cmp_eq_u32 s25, 1
	s_cselect_b64 s[16:17], -1, 0
	s_cmp_eq_u32 s25, 2
	s_cselect_b64 s[4:5], -1, 0
	s_cmp_eq_u32 s25, 3
	s_cselect_b64 s[6:7], -1, 0
	s_cmp_eq_u32 s25, 4
	v_xor_b32_e32 v28, 0x80000000, v28
	s_cselect_b64 s[8:9], -1, 0
	s_cmp_eq_u32 s25, 5
	v_cvt_pk_bf16_f32 v8, v8, v28
	v_xor_b32_e32 v28, 0x80000000, v29
	s_cselect_b64 s[10:11], -1, 0
	s_cmp_eq_u32 s25, 6
	v_cvt_pk_bf16_f32 v9, v9, v28
	v_xor_b32_e32 v28, 0x80000000, v30
	s_cselect_b64 s[12:13], -1, 0
	s_cmp_eq_u32 s25, 7
	s_mul_i32 s27, s2, 0xa00000
	v_cvt_pk_bf16_f32 v10, v10, v28
	v_xor_b32_e32 v28, 0x80000000, v31
	s_cselect_b64 s[14:15], -1, 0
	v_or_b32_e32 v22, 2, v20
	v_or_b32_e32 v23, 3, v20
	s_mul_hi_i32 s26, s2, 0xa00000
	s_or_b32 s21, s27, s21
	v_cvt_pk_bf16_f32 v11, v11, v28
	v_xor_b32_e32 v28, 0x80000000, v115
	v_mov_b32_e32 v115, v142
	v_lshl_or_b32 v223, v22, 4, v136
	v_lshl_or_b32 v225, v23, 4, v136
	v_lshlrev_b32_e32 v142, 6, v22
	v_lshlrev_b32_e32 v144, 6, v23
	v_mov_b32_e32 v22, s21
	v_mov_b32_e32 v23, s26
	v_mov_b32_e32 v220, v102
	v_mov_b32_e32 v221, v219
	v_pk_mul_f32 v[104:105], v[70:71], v[100:101] op_sel_hi:[0,1]
	v_xor_b32_e32 v24, 0x80000000, v24
	v_or_b32_e32 v21, 1, v20
	v_mad_i64_i32 v[22:23], s[26:27], v134, s56, v[22:23]
	v_pk_fma_f32 v[102:103], v[68:69], v[220:221], v[104:105] op_sel_hi:[0,1,1]
	v_pk_fma_f32 v[104:105], v[68:69], v[220:221], v[104:105] op_sel_hi:[0,1,1] neg_lo:[0,0,1] neg_hi:[0,0,1]
	v_xor_b32_e32 v32, 0x80000000, v32
	v_cvt_pk_bf16_f32 v12, v12, v24
	v_xor_b32_e32 v24, 0x80000000, v25
	v_mov_b32_e32 v29, v112
	v_mov_b32_e32 v111, v128
	v_xor_b32_e32 v112, 0x80000000, v141
	v_pk_add_f32 v[128:129], v[220:221], 0 neg_lo:[1,1] neg_hi:[1,1]
	v_lshl_or_b32 v221, v21, 4, v136
	v_lshlrev_b32_e32 v141, 6, v21
	v_and_b32_e32 v21, 3, v133
	v_readlane_b32 s26, v253, 46
	v_cvt_pk_bf16_f32 v4, v4, v32
	v_xor_b32_e32 v32, 0x80000000, v33
	v_cvt_pk_bf16_f32 v13, v13, v24
	v_xor_b32_e32 v24, 0x80000000, v26
	v_lshl_or_b32 v22, v21, 3, v22
	v_readlane_b32 s27, v253, 47
	v_ashrrev_i32_e32 v21, 31, v20
	v_cvt_pk_bf16_f32 v5, v5, v32
	v_xor_b32_e32 v32, 0x80000000, v34
	v_cvt_pk_bf16_f32 v14, v14, v24
	v_xor_b32_e32 v24, 0x80000000, v27
	v_mov_b32_e32 v113, v138
	v_mov_b32_e32 v129, v219
	v_lshl_or_b32 v219, v20, 4, v136
	v_lshlrev_b32_e32 v138, 6, v20
	v_lshl_add_u64 v[134:135], s[26:27], 0, v[22:23]
	s_lshl_b64 s[26:27], s[2:3], 24
	v_lshlrev_b64 v[20:21], 13, v[20:21]
	v_mov_b32_e32 v106, v102
	v_mov_b32_e32 v107, v105
	v_cvt_pk_bf16_f32 v6, v6, v32
	v_xor_b32_e32 v32, 0x80000000, v35
	v_cvt_pk_bf16_f32 v15, v15, v24
	v_lshlrev_b32_e32 v24, 2, v110
	v_lshl_add_u64 v[20:21], s[26:27], 0, v[20:21]
	v_mov_b32_e32 v132, 0
	v_cvt_pk_bf16_f32 v7, v7, v32
	v_xor_b32_e32 v70, 0x80000000, v71
	v_sub_u32_e32 v139, v218, v24
	v_and_b32_e32 v143, 48, v133
	s_mulk_i32 s25, 0x1100
	v_xor_b32_e32 v32, 0x80000000, v123
	v_xor_b32_e32 v34, 0x80000000, v127
	v_mov_b32_e32 v35, v124
	v_xor_b32_e32 v110, 0x80000000, v131
	v_pk_add_f32 v[122:123], v[172:173], 0 neg_lo:[1,1] neg_hi:[1,1]
	v_pk_add_f32 v[124:125], v[176:177], 0 neg_lo:[1,1] neg_hi:[1,1]
	v_pk_add_f32 v[126:127], v[190:191], 0 neg_lo:[1,1] neg_hi:[1,1]
	v_pk_add_f32 v[130:131], v[106:107], 0 neg_lo:[1,1] neg_hi:[1,1]
	v_or3_b32 v20, v20, s20, v148
	s_mov_b32 s23, 0
	s_waitcnt vmcnt(0)
	v_lshlrev_b32_e32 v0, 16, v2
	v_and_b32_e32 v1, 0xffff0000, v2
	v_lshlrev_b32_e32 v2, 16, v3
	v_and_b32_e32 v3, 0xffff0000, v3
	v_mov_b32_e32 v39, v43
	v_mov_b32_e32 v42, v68
	v_mov_b32_e32 v43, v68
	v_pk_mov_b32 v[108:109], v[104:105], v[102:103] op_sel:[1,0]
	v_lshlrev_b32_e32 v25, 4, v133
	v_mov_b32_e32 v26, v70
	v_mov_b32_e32 v27, v68
	v_xor_b32_e32 v30, 0x80000000, v119
	v_mov_b32_e32 v31, v116
	v_mov_b32_e32 v33, v120
	v_xor_b32_e32 v114, 0x80000000, v145
	v_xor_b32_e32 v116, 0x80000000, v161
	v_mov_b32_e32 v117, v146
	v_xor_b32_e32 v118, 0x80000000, v165
	v_mov_b32_e32 v119, v162
	v_xor_b32_e32 v120, 0x80000000, v169
	v_mov_b32_e32 v121, v166
	v_mov_b32_e32 v123, v171
	v_mov_b32_e32 v125, v175
	v_mov_b32_e32 v127, v189
	v_mov_b32_e32 v131, v105
	v_lshl_add_u32 v220, v219, 2, 0
	v_lshl_add_u32 v222, v221, 2, 0
	v_lshl_add_u32 v224, v223, 2, 0
	v_lshl_add_u32 v226, v225, 2, 0
	v_mov_b32_e32 v104, v105
	v_mov_b32_e32 v103, v102
	v_lshl_add_u64 v[136:137], s[62:63], 0, v[20:21]
	s_mov_b64 s[20:21], 0
	v_add_u32_e32 v148, s25, v139
	v_add_u32_e32 v227, v140, v143
	v_add_u32_e32 v228, 0, v138
	v_add_u32_e32 v229, 0, v141
	v_add_u32_e32 v230, 0, v142
	v_add_u32_e32 v231, 0, v144
	v_mov_b32_e32 v133, v132
	s_branch .LBB0_101
; #define LAS __attribute__((address_space(3)))
; __device__ __forceinline__ f32x4 ldbf4(const bf16_t* p) { const u32x2 w = *(const u32x2*)p; return (f32x4){bf_lo(w.x), bf_hi(w.x), bf_lo(w.y), bf_hi(w.y)}; }
; template <bool SAMPLE>
; __device__ __forceinline__ void ssm_item(kp_t kp, LAS unsigned char* lds, int l, int item, const bf16_t* Z, float* YM, int tid, int lane, int wave) {
;     ...
;         LAS float* U = Ub + (ch & 1) * 2048;
;         *(LAS f32x4*)(U + tid * 4) = ureg;
;         if (ch < NCH - 1) ureg = ldbf4(zsrc + (size_t)(ch + 1) * 128 * INW);
;         __syncthreads();
;         f32x2 hl[16]; f32x2 h = (f32x2){0.f, 0.f};
; #pragma unroll
;         for (int tt = 0; tt < 16; ++tt) { const LAS f32x4* up = (const LAS f32x4*)(U + (wave * 16 + tt) * 16);
;             if (SAMPLE && (tt & 3) == 0) h = h0[tt >> 2];
;             f32x2 bu = (f32x2){0.f, 0.f};
; #pragma unroll
;             for (int q = 0; q < 4; ++q) { const f32x4 u = up[q];
; #pragma unroll
;                 for (int e = 0; e < 4; ++e) bu = __builtin_elementwise_fma(B2[4 * q + e], (f32x2){u[e], u[e]}, bu); }
;             const f32x2 t1 = __builtin_elementwise_fma((f32x2){lr, lr}, h, bu);
;             h = __builtin_elementwise_fma((f32x2){-li, li}, (f32x2){h.y, h.x}, t1); hl[tt] = h;
.LBB0_100:
	s_add_i32 s25, s3, s24
	v_and_b32_e32 v254, 3, v184
	v_lshl_add_u32 v254, v254, 6, s25
	s_waitcnt lgkmcnt(0)
	ds_read_b128 v[20:23], v254
	ds_read_b64 v[244:245], v254 offset:16
	ds_read_b64 v[248:249], v254 offset:24
	ds_read_b128 v[174:177], v254 offset:32
	ds_read_b128 v[188:191], v254 offset:48
	v_cndmask_b32_e64 v247, 0, v133, s[0:1]
	v_mul_f32_e32 v246, v107, v133
	s_waitcnt lgkmcnt(2)
	v_mfma_f32_4x4x1_16b_f32 v[232:235], v20, v72, 0
	v_mfma_f32_4x4x1_16b_f32 v[236:239], v20, v73, 0
	s_nop 0
	v_mfma_f32_4x4x1_16b_f32 v[232:235], v21, v64, v[232:235]
	v_mfma_f32_4x4x1_16b_f32 v[236:239], v21, v65, v[236:239]
	s_nop 0
	v_mfma_f32_4x4x1_16b_f32 v[232:235], v22, v60, v[232:235]
	v_mfma_f32_4x4x1_16b_f32 v[236:239], v22, v61, v[236:239]
	s_nop 0
	v_mfma_f32_4x4x1_16b_f32 v[232:235], v23, v62, v[232:235]
	v_mfma_f32_4x4x1_16b_f32 v[236:239], v23, v63, v[236:239]
	s_nop 0
	v_mfma_f32_4x4x1_16b_f32 v[232:235], v244, v66, v[232:235]
	v_mfma_f32_4x4x1_16b_f32 v[236:239], v244, v67, v[236:239]
	s_nop 0
	v_mfma_f32_4x4x1_16b_f32 v[232:235], v245, v52, v[232:235]
	v_mfma_f32_4x4x1_16b_f32 v[236:239], v245, v53, v[236:239]
	s_nop 0
	v_mfma_f32_4x4x1_16b_f32 v[232:235], v248, v56, v[232:235]
	v_mfma_f32_4x4x1_16b_f32 v[236:239], v248, v57, v[236:239]
	s_nop 0
	v_mfma_f32_4x4x1_16b_f32 v[232:235], v249, v54, v[232:235]
	v_mfma_f32_4x4x1_16b_f32 v[236:239], v249, v55, v[236:239]
	s_nop 0
	ds_read_b128 v[20:23], v254 offset:256
	ds_read_b64 v[244:245], v254 offset:272
	ds_read_b64 v[248:249], v254 offset:280
	s_waitcnt lgkmcnt(3)
	v_mfma_f32_4x4x1_16b_f32 v[232:235], v174, v58, v[232:235]
	v_mfma_f32_4x4x1_16b_f32 v[236:239], v174, v59, v[236:239]
	s_nop 0
	v_mfma_f32_4x4x1_16b_f32 v[232:235], v175, v44, v[232:235]
	v_mfma_f32_4x4x1_16b_f32 v[236:239], v175, v45, v[236:239]
	s_nop 0
	v_mfma_f32_4x4x1_16b_f32 v[232:235], v176, v48, v[232:235]
	v_mfma_f32_4x4x1_16b_f32 v[236:239], v176, v49, v[236:239]
	s_nop 0
	v_mfma_f32_4x4x1_16b_f32 v[232:235], v177, v46, v[232:235]
	v_mfma_f32_4x4x1_16b_f32 v[236:239], v177, v47, v[236:239]
	s_nop 0
	v_mfma_f32_4x4x1_16b_f32 v[232:235], v188, v50, v[232:235]
	v_mfma_f32_4x4x1_16b_f32 v[236:239], v188, v51, v[236:239]
	s_nop 0
	v_mfma_f32_4x4x1_16b_f32 v[232:235], v189, v36, v[232:235]
	v_mfma_f32_4x4x1_16b_f32 v[236:239], v189, v37, v[236:239]
	s_nop 0
	v_mfma_f32_4x4x1_16b_f32 v[232:235], v190, v40, v[232:235]
	v_mfma_f32_4x4x1_16b_f32 v[236:239], v190, v41, v[236:239]
	s_nop 0
	v_mfma_f32_4x4x1_16b_f32 v[232:235], v191, v38, v[232:235]
	v_mfma_f32_4x4x1_16b_f32 v[236:239], v191, v39, v[236:239]
	s_nop 0
	ds_read_b128 v[174:177], v254 offset:288
	ds_read_b128 v[188:191], v254 offset:304
	s_nop 4
	v_fma_f32 v138, v42, 0, v232
	v_fma_f32 v139, v43, 0, v236
	v_fma_f32 v138, v70, 0, v138
	v_fma_f32 v139, v71, 0, v139
	v_fma_f32 v140, v42, v138, v233
	v_fma_f32 v141, v43, v139, v237
	v_fma_f32 v140, v70, v139, v140
	v_fma_f32 v141, v71, v138, v141
	v_fma_f32 v142, v42, v140, v234
	v_fma_f32 v143, v43, v141, v238
	v_fma_f32 v142, v70, v141, v142
	v_fma_f32 v143, v71, v140, v143
	v_fma_f32 v144, v42, v142, v235
	v_fma_f32 v145, v43, v143, v239
	v_fma_f32 v144, v70, v143, v144
	v_fma_f32 v145, v71, v142, v145
	s_waitcnt lgkmcnt(2)
	v_mfma_f32_4x4x1_16b_f32 v[232:235], v20, v72, 0
	v_mfma_f32_4x4x1_16b_f32 v[236:239], v20, v73, 0
	s_nop 0
	v_mfma_f32_4x4x1_16b_f32 v[232:235], v21, v64, v[232:235]
	v_mfma_f32_4x4x1_16b_f32 v[236:239], v21, v65, v[236:239]
	s_nop 0
	v_mfma_f32_4x4x1_16b_f32 v[232:235], v22, v60, v[232:235]
	v_mfma_f32_4x4x1_16b_f32 v[236:239], v22, v61, v[236:239]
	s_nop 0
	v_mfma_f32_4x4x1_16b_f32 v[232:235], v23, v62, v[232:235]
	v_mfma_f32_4x4x1_16b_f32 v[236:239], v23, v63, v[236:239]
	s_nop 0
	v_mfma_f32_4x4x1_16b_f32 v[232:235], v244, v66, v[232:235]
	v_mfma_f32_4x4x1_16b_f32 v[236:239], v244, v67, v[236:239]
	s_nop 0
	v_mfma_f32_4x4x1_16b_f32 v[232:235], v245, v52, v[232:235]
	v_mfma_f32_4x4x1_16b_f32 v[236:239], v245, v53, v[236:239]
	s_nop 0
	v_mfma_f32_4x4x1_16b_f32 v[232:235], v248, v56, v[232:235]
	v_mfma_f32_4x4x1_16b_f32 v[236:239], v248, v57, v[236:239]
	s_nop 0
	v_mfma_f32_4x4x1_16b_f32 v[232:235], v249, v54, v[232:235]
	v_mfma_f32_4x4x1_16b_f32 v[236:239], v249, v55, v[236:239]
	s_nop 0
	ds_read_b128 v[20:23], v254 offset:512
	ds_read_b64 v[244:245], v254 offset:528
	ds_read_b64 v[248:249], v254 offset:536
	s_waitcnt lgkmcnt(3)
	v_mfma_f32_4x4x1_16b_f32 v[232:235], v174, v58, v[232:235]
	v_mfma_f32_4x4x1_16b_f32 v[236:239], v174, v59, v[236:239]
	s_nop 0
	v_mfma_f32_4x4x1_16b_f32 v[232:235], v175, v44, v[232:235]
	v_mfma_f32_4x4x1_16b_f32 v[236:239], v175, v45, v[236:239]
	s_nop 0
	v_mfma_f32_4x4x1_16b_f32 v[232:235], v176, v48, v[232:235]
	v_mfma_f32_4x4x1_16b_f32 v[236:239], v176, v49, v[236:239]
	s_nop 0
	v_mfma_f32_4x4x1_16b_f32 v[232:235], v177, v46, v[232:235]
	v_mfma_f32_4x4x1_16b_f32 v[236:239], v177, v47, v[236:239]
	s_nop 0
	v_mfma_f32_4x4x1_16b_f32 v[232:235], v188, v50, v[232:235]
	v_mfma_f32_4x4x1_16b_f32 v[236:239], v188, v51, v[236:239]
	s_nop 0
	v_mfma_f32_4x4x1_16b_f32 v[232:235], v189, v36, v[232:235]
	v_mfma_f32_4x4x1_16b_f32 v[236:239], v189, v37, v[236:239]
	s_nop 0
	v_mfma_f32_4x4x1_16b_f32 v[232:235], v190, v40, v[232:235]
	v_mfma_f32_4x4x1_16b_f32 v[236:239], v190, v41, v[236:239]
	s_nop 0
	v_mfma_f32_4x4x1_16b_f32 v[232:235], v191, v38, v[232:235]
	v_mfma_f32_4x4x1_16b_f32 v[236:239], v191, v39, v[236:239]
	s_nop 0
	ds_read_b128 v[174:177], v254 offset:544
	ds_read_b128 v[188:191], v254 offset:560
	s_nop 4
	v_fma_f32 v146, v42, v144, v232
	v_fma_f32 v147, v43, v145, v236
	v_fma_f32 v146, v70, v145, v146
	v_fma_f32 v147, v71, v144, v147
	v_fma_f32 v160, v42, v146, v233
	v_fma_f32 v161, v43, v147, v237
	v_fma_f32 v160, v70, v147, v160
	v_fma_f32 v161, v71, v146, v161
	v_fma_f32 v162, v42, v160, v234
	v_fma_f32 v163, v43, v161, v238
	v_fma_f32 v162, v70, v161, v162
	v_fma_f32 v163, v71, v160, v163
	v_fma_f32 v164, v42, v162, v235
	v_fma_f32 v165, v43, v163, v239
	v_fma_f32 v164, v70, v163, v164
	v_fma_f32 v165, v71, v162, v165
	s_waitcnt lgkmcnt(2)
; #define LAS __attribute__((address_space(3)))
; template <bool SAMPLE>
; __device__ __forceinline__ void ssm_item(kp_t kp, LAS unsigned char* lds, int l, int item, const bf16_t* Z, float* YM, int tid, int lane, int wave) {
;     ...
;         for (int tt = 0; tt < 16; ++tt) { const LAS f32x4* up = (const LAS f32x4*)(U + (wave * 16 + tt) * 16);
;             if (SAMPLE && (tt & 3) == 0) h = h0[tt >> 2];
;             f32x2 bu = (f32x2){0.f, 0.f};
; #pragma unroll
;             for (int q = 0; q < 4; ++q) { const f32x4 u = up[q];
; #pragma unroll
;                 for (int e = 0; e < 4; ++e) bu = __builtin_elementwise_fma(B2[4 * q + e], (f32x2){u[e], u[e]}, bu); }
;             const f32x2 t1 = __builtin_elementwise_fma((f32x2){lr, lr}, h, bu);
;             h = __builtin_elementwise_fma((f32x2){-li, li}, (f32x2){h.y, h.x}, t1); hl[tt] = h;
;             if (SAMPLE && (tt & 3) == 3) { const size_t si = ((size_t)(l * 128 + b * 32 + wave * 4 + (tt >> 2)) * 64 + g) * 64 + p; OUTP[O_SRE + si] = h.x; OUTP[O_SIM + si] = h.y; } }
;         float cr_ = car, ci_ = cai, cwr = 0.f, cwi = 0.f;
;         if (!SAMPLE) {
;         Eb[wave * 64 + p] = h;
;         __syncthreads();
	v_mfma_f32_4x4x1_16b_f32 v[232:235], v20, v72, 0
	v_mfma_f32_4x4x1_16b_f32 v[236:239], v20, v73, 0
	s_nop 0
	v_mfma_f32_4x4x1_16b_f32 v[232:235], v21, v64, v[232:235]
	v_mfma_f32_4x4x1_16b_f32 v[236:239], v21, v65, v[236:239]
	s_nop 0
	v_mfma_f32_4x4x1_16b_f32 v[232:235], v22, v60, v[232:235]
	v_mfma_f32_4x4x1_16b_f32 v[236:239], v22, v61, v[236:239]
	s_nop 0
	v_mfma_f32_4x4x1_16b_f32 v[232:235], v23, v62, v[232:235]
	v_mfma_f32_4x4x1_16b_f32 v[236:239], v23, v63, v[236:239]
	s_nop 0
	v_mfma_f32_4x4x1_16b_f32 v[232:235], v244, v66, v[232:235]
	v_mfma_f32_4x4x1_16b_f32 v[236:239], v244, v67, v[236:239]
	s_nop 0
	v_mfma_f32_4x4x1_16b_f32 v[232:235], v245, v52, v[232:235]
	v_mfma_f32_4x4x1_16b_f32 v[236:239], v245, v53, v[236:239]
	s_nop 0
	v_mfma_f32_4x4x1_16b_f32 v[232:235], v248, v56, v[232:235]
	v_mfma_f32_4x4x1_16b_f32 v[236:239], v248, v57, v[236:239]
	s_nop 0
	v_mfma_f32_4x4x1_16b_f32 v[232:235], v249, v54, v[232:235]
	v_mfma_f32_4x4x1_16b_f32 v[236:239], v249, v55, v[236:239]
	s_nop 0
	ds_read_b128 v[20:23], v254 offset:768
	ds_read_b64 v[244:245], v254 offset:784
	ds_read_b64 v[248:249], v254 offset:792
	s_waitcnt lgkmcnt(3)
	v_mfma_f32_4x4x1_16b_f32 v[232:235], v174, v58, v[232:235]
	v_mfma_f32_4x4x1_16b_f32 v[236:239], v174, v59, v[236:239]
	s_nop 0
	v_mfma_f32_4x4x1_16b_f32 v[232:235], v175, v44, v[232:235]
	v_mfma_f32_4x4x1_16b_f32 v[236:239], v175, v45, v[236:239]
	s_nop 0
	v_mfma_f32_4x4x1_16b_f32 v[232:235], v176, v48, v[232:235]
	v_mfma_f32_4x4x1_16b_f32 v[236:239], v176, v49, v[236:239]
	s_nop 0
	v_mfma_f32_4x4x1_16b_f32 v[232:235], v177, v46, v[232:235]
	v_mfma_f32_4x4x1_16b_f32 v[236:239], v177, v47, v[236:239]
	s_nop 0
	v_mfma_f32_4x4x1_16b_f32 v[232:235], v188, v50, v[232:235]
	v_mfma_f32_4x4x1_16b_f32 v[236:239], v188, v51, v[236:239]
	s_nop 0
	v_mfma_f32_4x4x1_16b_f32 v[232:235], v189, v36, v[232:235]
	v_mfma_f32_4x4x1_16b_f32 v[236:239], v189, v37, v[236:239]
	s_nop 0
	v_mfma_f32_4x4x1_16b_f32 v[232:235], v190, v40, v[232:235]
	v_mfma_f32_4x4x1_16b_f32 v[236:239], v190, v41, v[236:239]
	s_nop 0
	v_mfma_f32_4x4x1_16b_f32 v[232:235], v191, v38, v[232:235]
	v_mfma_f32_4x4x1_16b_f32 v[236:239], v191, v39, v[236:239]
	s_nop 0
	ds_read_b128 v[174:177], v254 offset:800
	ds_read_b128 v[188:191], v254 offset:816
	s_nop 4
	v_fma_f32 v166, v42, v164, v232
	v_fma_f32 v167, v43, v165, v236
	v_fma_f32 v166, v70, v165, v166
	v_fma_f32 v167, v71, v164, v167
	v_fma_f32 v168, v42, v166, v233
	v_fma_f32 v169, v43, v167, v237
	v_fma_f32 v168, v70, v167, v168
	v_fma_f32 v169, v71, v166, v169
	v_fma_f32 v170, v42, v168, v234
	v_fma_f32 v171, v43, v169, v238
	v_fma_f32 v170, v70, v169, v170
	v_fma_f32 v171, v71, v168, v171
	v_fma_f32 v172, v42, v170, v235
	v_fma_f32 v173, v43, v171, v239
	v_fma_f32 v172, v70, v171, v172
	v_fma_f32 v173, v71, v170, v173
	s_waitcnt lgkmcnt(2)
	v_mfma_f32_4x4x1_16b_f32 v[232:235], v20, v72, 0
	v_mfma_f32_4x4x1_16b_f32 v[236:239], v20, v73, 0
	s_nop 0
	v_mfma_f32_4x4x1_16b_f32 v[232:235], v21, v64, v[232:235]
	v_mfma_f32_4x4x1_16b_f32 v[236:239], v21, v65, v[236:239]
	s_nop 0
	v_mfma_f32_4x4x1_16b_f32 v[232:235], v22, v60, v[232:235]
	v_mfma_f32_4x4x1_16b_f32 v[236:239], v22, v61, v[236:239]
	s_nop 0
	v_mfma_f32_4x4x1_16b_f32 v[232:235], v23, v62, v[232:235]
	v_mfma_f32_4x4x1_16b_f32 v[236:239], v23, v63, v[236:239]
	s_nop 0
	v_mfma_f32_4x4x1_16b_f32 v[232:235], v244, v66, v[232:235]
	v_mfma_f32_4x4x1_16b_f32 v[236:239], v244, v67, v[236:239]
	s_nop 0
	v_mfma_f32_4x4x1_16b_f32 v[232:235], v245, v52, v[232:235]
	v_mfma_f32_4x4x1_16b_f32 v[236:239], v245, v53, v[236:239]
	s_nop 0
	v_mfma_f32_4x4x1_16b_f32 v[232:235], v248, v56, v[232:235]
	v_mfma_f32_4x4x1_16b_f32 v[236:239], v248, v57, v[236:239]
	s_nop 0
	v_mfma_f32_4x4x1_16b_f32 v[232:235], v249, v54, v[232:235]
	v_mfma_f32_4x4x1_16b_f32 v[236:239], v249, v55, v[236:239]
	s_nop 0
	s_waitcnt lgkmcnt(0)
	v_mfma_f32_4x4x1_16b_f32 v[232:235], v174, v58, v[232:235]
	v_mfma_f32_4x4x1_16b_f32 v[236:239], v174, v59, v[236:239]
	s_nop 0
	v_mfma_f32_4x4x1_16b_f32 v[232:235], v175, v44, v[232:235]
	v_mfma_f32_4x4x1_16b_f32 v[236:239], v175, v45, v[236:239]
	s_nop 0
	v_mfma_f32_4x4x1_16b_f32 v[232:235], v176, v48, v[232:235]
	v_mfma_f32_4x4x1_16b_f32 v[236:239], v176, v49, v[236:239]
	s_nop 0
	v_mfma_f32_4x4x1_16b_f32 v[232:235], v177, v46, v[232:235]
	v_mfma_f32_4x4x1_16b_f32 v[236:239], v177, v47, v[236:239]
	s_nop 0
	v_mfma_f32_4x4x1_16b_f32 v[232:235], v188, v50, v[232:235]
	v_mfma_f32_4x4x1_16b_f32 v[236:239], v188, v51, v[236:239]
	s_nop 0
	v_mfma_f32_4x4x1_16b_f32 v[232:235], v189, v36, v[232:235]
	v_mfma_f32_4x4x1_16b_f32 v[236:239], v189, v37, v[236:239]
	s_nop 0
	v_mfma_f32_4x4x1_16b_f32 v[232:235], v190, v40, v[232:235]
	v_mfma_f32_4x4x1_16b_f32 v[236:239], v190, v41, v[236:239]
	s_nop 0
	v_mfma_f32_4x4x1_16b_f32 v[232:235], v191, v38, v[232:235]
	v_mfma_f32_4x4x1_16b_f32 v[236:239], v191, v39, v[236:239]
	s_nop 0
	s_nop 4
	v_fma_f32 v174, v42, v172, v232
	v_fma_f32 v175, v43, v173, v236
	v_fma_f32 v174, v70, v173, v174
	v_fma_f32 v175, v71, v172, v175
	v_fma_f32 v176, v42, v174, v233
	v_fma_f32 v177, v43, v175, v237
	v_fma_f32 v176, v70, v175, v176
	v_fma_f32 v177, v71, v174, v177
	v_fma_f32 v188, v42, v176, v234
	v_fma_f32 v189, v43, v177, v238
	v_fma_f32 v188, v70, v177, v188
	v_fma_f32 v189, v71, v176, v189
	v_fma_f32 v190, v42, v188, v235
	v_fma_f32 v191, v43, v189, v239
	v_fma_f32 v190, v70, v189, v190
	v_fma_f32 v191, v71, v188, v191
	v_cndmask_b32_e64 v22, 0, v132, s[0:1]
	ds_write_b64 v217, v[190:191] offset:16384
	s_waitcnt lgkmcnt(0)
	s_barrier
; template <bool SAMPLE>
; __device__ __forceinline__ void ssm_item(kp_t kp, LAS unsigned char* lds, int l, int item, const bf16_t* Z, float* YM, int tid, int lane, int wave) {
;     ...
;         Eb[wave * 64 + p] = h;
;         __syncthreads();
; #pragma unroll
;         for (int v = 0; v < 8; ++v) { if (v == wave) { cwr = cr_; cwi = ci_; } const f32x2 e = Eb[v * 64 + p];
;             const float nr = l16r * cr_ - l16i * ci_ + e.x, ni = l16r * ci_ + l16i * cr_ + e.y; cr_ = nr; ci_ = ni; }
;         car = cr_; cai = ci_;
	ds_read2st64_b64 v[232:235], v218 offset0:32 offset1:33
	ds_read2st64_b64 v[236:239], v218 offset0:34 offset1:35
	v_mul_f32_e32 v20, v109, v133
	v_pk_fma_f32 v[20:21], v[108:109], v[132:133], v[20:21] op_sel_hi:[1,1,0] neg_lo:[0,0,1] neg_hi:[0,0,1]
	v_pk_fma_f32 v[132:133], v[106:107], v[132:133], v[246:247] op_sel_hi:[1,1,0]
	s_waitcnt lgkmcnt(1)
	v_pk_add_f32 v[244:245], v[20:21], v[232:233]
	v_pk_add_f32 v[132:133], v[132:133], v[232:233] op_sel:[0,1] op_sel_hi:[1,0]
	v_cndmask_b32_e64 v248, v22, v244, s[16:17]
	v_cndmask_b32_e64 v246, v247, v132, s[16:17]
	v_pk_mul_f32 v[132:133], v[106:107], v[132:133] op_sel_hi:[1,0]
	ds_read2st64_b64 v[240:243], v218 offset0:36 offset1:37
	ds_read2st64_b64 v[20:23], v218 offset0:38 offset1:39
	v_add_u32_e32 v217, s84, v217
	v_add_u32_e32 v218, s84, v218
	s_sub_i32 s84, 0, s84
	v_pk_fma_f32 v[232:233], v[108:109], v[244:245], v[132:133] neg_lo:[0,0,1] neg_hi:[0,0,1]
	v_pk_fma_f32 v[132:133], v[108:109], v[244:245], v[132:133] op_sel_hi:[1,0,1]
	s_nop 0
	v_mov_b32_e32 v233, v133
	v_pk_add_f32 v[132:133], v[234:235], v[232:233]
	s_nop 0
	v_cndmask_b32_e64 v235, v248, v132, s[4:5]
	v_mul_f32_e32 v232, v109, v133
	v_mul_f32_e32 v234, v106, v132
	v_cndmask_b32_e64 v244, v246, v133, s[4:5]
	v_pk_fma_f32 v[232:233], v[108:109], v[132:133], v[232:233] op_sel_hi:[1,1,0] neg_lo:[0,0,1] neg_hi:[0,0,1]
	v_pk_fma_f32 v[132:133], v[106:107], v[132:133], v[234:235] op_sel_hi:[1,1,0]
	s_nop 0
	v_mov_b32_e32 v233, v133
	s_waitcnt lgkmcnt(2)
	v_pk_add_f32 v[132:133], v[236:237], v[232:233]
	s_nop 0
	v_pk_mul_f32 v[232:233], v[102:103], v[132:133]
	v_cndmask_b32_e64 v236, v235, v132, s[6:7]
	v_cndmask_b32_e64 v237, v244, v133, s[6:7]
	v_pk_fma_f32 v[234:235], v[104:105], v[132:133], v[232:233] op_sel:[0,0,1] op_sel_hi:[1,1,0] neg_lo:[0,0,1] neg_hi:[0,0,1]
	v_pk_fma_f32 v[132:133], v[104:105], v[132:133], v[232:233] op_sel:[0,0,1] op_sel_hi:[1,1,0]
	s_nop 0
	v_mov_b32_e32 v235, v133
	v_pk_add_f32 v[132:133], v[238:239], v[234:235]
	s_nop 0
	v_pk_mul_f32 v[232:233], v[102:103], v[132:133]
	v_cndmask_b32_e64 v236, v236, v132, s[8:9]
	v_cndmask_b32_e64 v237, v237, v133, s[8:9]
	v_pk_fma_f32 v[234:235], v[104:105], v[132:133], v[232:233] op_sel:[0,0,1] op_sel_hi:[1,1,0] neg_lo:[0,0,1] neg_hi:[0,0,1]
	v_pk_fma_f32 v[132:133], v[104:105], v[132:133], v[232:233] op_sel:[0,0,1] op_sel_hi:[1,1,0]
	s_nop 0
	v_mov_b32_e32 v235, v133
	s_waitcnt lgkmcnt(1)
	v_pk_add_f32 v[132:133], v[240:241], v[234:235]
	s_nop 0
	v_pk_mul_f32 v[232:233], v[102:103], v[132:133]
	v_cndmask_b32_e64 v236, v236, v132, s[10:11]
	v_cndmask_b32_e64 v237, v237, v133, s[10:11]
	v_pk_fma_f32 v[234:235], v[104:105], v[132:133], v[232:233] op_sel:[0,0,1] op_sel_hi:[1,1,0] neg_lo:[0,0,1] neg_hi:[0,0,1]
	v_pk_fma_f32 v[132:133], v[104:105], v[132:133], v[232:233] op_sel:[0,0,1] op_sel_hi:[1,1,0]
	s_nop 0
	v_mov_b32_e32 v235, v133
	v_pk_add_f32 v[232:233], v[242:243], v[234:235]
	s_nop 0
	v_mul_f32_e32 v132, v109, v233
	v_cndmask_b32_e64 v235, v236, v232, s[12:13]
	v_pk_fma_f32 v[132:133], v[108:109], v[232:233], v[132:133] op_sel_hi:[1,1,0] neg_lo:[0,0,1] neg_hi:[0,0,1]
	v_mul_f32_e32 v234, v107, v233
	v_cndmask_b32_e64 v236, v237, v233, s[12:13]
	s_waitcnt lgkmcnt(0)
	v_pk_add_f32 v[132:133], v[20:21], v[132:133]
	v_pk_fma_f32 v[232:233], v[106:107], v[232:233], v[234:235] op_sel_hi:[1,1,0]
	s_nop 0
	v_pk_add_f32 v[20:21], v[20:21], v[232:233] op_sel:[1,0] op_sel_hi:[0,1]
	v_cndmask_b32_e64 v232, v235, v132, s[14:15]
	v_cndmask_b32_e64 v234, v236, v20, s[14:15]
	v_pk_fma_f32 v[138:139], v[68:69], v[232:233], v[138:139] op_sel_hi:[1,0,1]
	v_pk_mul_f32 v[20:21], v[106:107], v[20:21] op_sel_hi:[1,0]
	v_pk_fma_f32 v[138:139], v[26:27], v[234:235], v[138:139] op_sel_hi:[1,0,1]
	s_nop 0
	v_cvt_pk_bf16_f32 v233, v138, v139
	s_nop 0
	v_pk_fma_f32 v[138:139], v[74:75], v[232:233], v[140:141] op_sel_hi:[1,0,1]
	v_add_u32_e32 v140, 0x5000, v148
	v_pk_fma_f32 v[138:139], v[28:29], v[234:235], v[138:139] op_sel_hi:[1,0,1]
	s_nop 0
	v_cvt_pk_bf16_f32 v138, v138, v139
	ds_write2_b32 v140, v233, v138 offset1:68
	v_pk_fma_f32 v[138:139], v[76:77], v[232:233], v[142:143] op_sel_hi:[1,0,1]
	s_nop 0
	v_pk_fma_f32 v[138:139], v[30:31], v[234:235], v[138:139] op_sel_hi:[1,0,1]
	s_nop 0
	v_cvt_pk_bf16_f32 v141, v138, v139
	v_pk_fma_f32 v[138:139], v[78:79], v[232:233], v[144:145] op_sel_hi:[1,0,1]
	s_nop 0
	v_pk_fma_f32 v[138:139], v[32:33], v[234:235], v[138:139] op_sel_hi:[1,0,1]
	s_nop 0
	v_cvt_pk_bf16_f32 v138, v138, v139
	ds_write2_b32 v140, v141, v138 offset0:136 offset1:204
	v_pk_fma_f32 v[138:139], v[80:81], v[232:233], v[146:147] op_sel_hi:[1,0,1]
	v_add_u32_e32 v141, 0x5400, v148
	v_pk_fma_f32 v[138:139], v[34:35], v[234:235], v[138:139] op_sel_hi:[1,0,1]
	v_lshl_add_u32 v146, v219, 2, s3
	v_cvt_pk_bf16_f32 v140, v138, v139
	v_pk_fma_f32 v[138:139], v[82:83], v[232:233], v[160:161] op_sel_hi:[1,0,1]
	s_nop 0
	v_pk_fma_f32 v[138:139], v[110:111], v[234:235], v[138:139] op_sel_hi:[1,0,1]
	s_nop 0
	v_cvt_pk_bf16_f32 v138, v138, v139
	ds_write2_b32 v141, v140, v138 offset0:16 offset1:84
	v_pk_fma_f32 v[138:139], v[84:85], v[232:233], v[162:163] op_sel_hi:[1,0,1]
	s_nop 0
	v_pk_fma_f32 v[138:139], v[112:113], v[234:235], v[138:139] op_sel_hi:[1,0,1]
	s_nop 0
	v_cvt_pk_bf16_f32 v140, v138, v139
	v_pk_fma_f32 v[138:139], v[86:87], v[232:233], v[164:165] op_sel_hi:[1,0,1]
	s_nop 0
	v_pk_fma_f32 v[138:139], v[114:115], v[234:235], v[138:139] op_sel_hi:[1,0,1]
	s_nop 0
	v_cvt_pk_bf16_f32 v138, v138, v139
	ds_write2_b32 v141, v140, v138 offset0:152 offset1:220
	v_pk_fma_f32 v[138:139], v[88:89], v[232:233], v[166:167] op_sel_hi:[1,0,1]
	v_add_u32_e32 v141, 0x5800, v148
; #define LAS __attribute__((address_space(3)))
; __device__ __forceinline__ unsigned cvt_pk_bf16(float lo, float hi) { unsigned r; asm("v_cvt_pk_bf16_f32 %0, %1, %2" : "=v"(r) : "v"(lo), "v"(hi)); return r; }
; #define LDS_WAIT() asm volatile("s_waitcnt lgkmcnt(0)" ::: "memory")
; template <bool SAMPLE>
; __device__ __forceinline__ void ssm_item(kp_t kp, LAS unsigned char* lds, int l, int item, const bf16_t* Z, float* YM, int tid, int lane, int wave) {
;     ...
;         for (int tt = 0; tt < 16; ++tt) {
;             const f32x2 t1 = __builtin_elementwise_fma(pw[tt], (f32x2){cwr, cwr}, hl[tt]);
;             const f32x2 h2 = __builtin_elementwise_fma((f32x2){-pw[tt].y, pw[tt].x}, (f32x2){cwi, cwi}, t1);
;             *(LAS unsigned*)(Hb + (wave * 16 + tt) * 272 + p * 4) = cvt_pk_bf16(h2.x, h2.y); }
;         LDS_WAIT();
;         f32x4 acc = (f32x4){0.f, 0.f, 0.f, 0.f};
; #pragma unroll
;         for (int ks = 0; ks < 4; ++ks) { const bf16x8 av = *(const LAS bf16x8*)(Hb + (wave * 16 + fr) * 272 + (ks * 32 + fq * 8) * 2);
;             acc = __builtin_amdgcn_mfma_f32_16x16x32_bf16(av, cf[ks], acc, 0, 0, 0); }
;         float yv[4];
; #pragma unroll
;         for (int j = 0; j < 4; ++j) { const int t = wave * 16 + fq * 4 + j; float y = acc[j] + Dv * U[t * 16 + fr]; y = gelu_tanh(y); yv[j] = y; Yb[t * 16 + fr] = y; }
	v_pk_fma_f32 v[138:139], v[116:117], v[234:235], v[138:139] op_sel_hi:[1,0,1]
	s_nop 0
	v_cvt_pk_bf16_f32 v140, v138, v139
	v_pk_fma_f32 v[138:139], v[90:91], v[232:233], v[168:169] op_sel_hi:[1,0,1]
	s_nop 0
	v_pk_fma_f32 v[138:139], v[118:119], v[234:235], v[138:139] op_sel_hi:[1,0,1]
	s_nop 0
	v_cvt_pk_bf16_f32 v138, v138, v139
	ds_write2_b32 v141, v140, v138 offset0:32 offset1:100
	v_pk_fma_f32 v[138:139], v[92:93], v[232:233], v[170:171] op_sel_hi:[1,0,1]
	s_nop 0
	v_pk_fma_f32 v[138:139], v[120:121], v[234:235], v[138:139] op_sel_hi:[1,0,1]
	s_nop 0
	v_cvt_pk_bf16_f32 v140, v138, v139
	v_pk_fma_f32 v[138:139], v[94:95], v[232:233], v[172:173] op_sel_hi:[1,0,1]
	s_nop 0
	v_pk_fma_f32 v[138:139], v[122:123], v[234:235], v[138:139] op_sel_hi:[1,0,1]
	s_nop 0
	v_cvt_pk_bf16_f32 v138, v138, v139
	ds_write2_b32 v141, v140, v138 offset0:168 offset1:236
	v_pk_fma_f32 v[138:139], v[96:97], v[232:233], v[174:175] op_sel_hi:[1,0,1]
	v_add_u32_e32 v141, 0x5c00, v148
	v_pk_fma_f32 v[138:139], v[124:125], v[234:235], v[138:139] op_sel_hi:[1,0,1]
	s_nop 0
	v_cvt_pk_bf16_f32 v140, v138, v139
	v_pk_fma_f32 v[138:139], v[98:99], v[232:233], v[176:177] op_sel_hi:[1,0,1]
	s_nop 0
	v_pk_fma_f32 v[138:139], v[126:127], v[234:235], v[138:139] op_sel_hi:[1,0,1]
	s_nop 0
	v_cvt_pk_bf16_f32 v138, v138, v139
	ds_write2_b32 v141, v140, v138 offset0:48 offset1:116
	v_pk_fma_f32 v[138:139], v[100:101], v[232:233], v[188:189] op_sel_hi:[1,0,1]
	s_nop 0
	v_pk_fma_f32 v[138:139], v[128:129], v[234:235], v[138:139] op_sel_hi:[1,0,1]
	s_nop 0
	v_cvt_pk_bf16_f32 v140, v138, v139
	v_pk_fma_f32 v[138:139], v[108:109], v[232:233], v[190:191] op_sel_hi:[1,0,1]
	s_nop 0
	v_pk_fma_f32 v[138:139], v[130:131], v[234:235], v[138:139] op_sel_hi:[1,0,1]
	s_nop 0
	v_cvt_pk_bf16_f32 v138, v138, v139
	ds_write2_b32 v141, v140, v138 offset0:184 offset1:252
	s_waitcnt lgkmcnt(0)
	ds_read_b128 v[138:141], v227 offset:20480
	ds_read_b128 v[142:145], v227 offset:20544
	s_waitcnt lgkmcnt(1)
	v_mfma_f32_16x16x32_bf16 v[138:141], v[138:141], v[4:7], 0
	ds_read_b128 v[160:163], v227 offset:20608
	ds_read_b32 v146, v146
	s_waitcnt lgkmcnt(2)
	v_mfma_f32_16x16x32_bf16 v[138:141], v[142:145], v[8:11], v[138:141]
	ds_read_b128 v[142:145], v227 offset:20672
	s_waitcnt lgkmcnt(2)
	v_mfma_f32_16x16x32_bf16 v[138:141], v[160:163], v[12:15], v[138:141]
	s_waitcnt lgkmcnt(0)
	v_mfma_f32_16x16x32_bf16 v[138:141], v[142:145], v[16:19], v[138:141]
	s_nop 7
	v_fma_f32 v138, v200, v146, v138
	v_mul_f32_e32 v142, 0x3d372713, v138
	v_mul_f32_e32 v142, v138, v142
	v_fma_f32 v142, v138, v142, v138
	v_mul_f32_e32 v142, 0x3f4c422a, v142
	v_add_f32_e32 v142, v142, v142
	v_mul_f32_e32 v142, 0x3fb8aa3b, v142
	v_exp_f32_e32 v142, v142
	v_mul_f32_e32 v138, 0.5, v138
	v_add_f32_e32 v142, 1.0, v142
	v_div_scale_f32 v143, s[26:27], v142, v142, 2.0
	v_rcp_f32_e32 v144, v143
	s_nop 0
	v_fma_f32 v145, -v143, v144, 1.0
	v_fmac_f32_e32 v144, v145, v144
	v_div_scale_f32 v145, vcc, 2.0, v142, 2.0
	v_mul_f32_e32 v146, v145, v144
	v_fma_f32 v147, -v143, v146, v145
	v_fmac_f32_e32 v146, v147, v144
	v_fma_f32 v143, -v143, v146, v145
	v_div_fmas_f32 v143, v143, v144, v146
	v_div_fixup_f32 v142, v143, v142, 2.0
	v_sub_f32_e32 v142, 1.0, v142
	v_add_f32_e32 v142, 1.0, v142
	v_mul_f32_e32 v168, v138, v142
	ds_write_b32 v220, v168 offset:55296
	v_lshl_add_u32 v138, v221, 2, s3
	ds_read_b32 v138, v138
	s_waitcnt lgkmcnt(0)
	v_fma_f32 v138, v200, v138, v139
	v_mul_f32_e32 v139, 0x3d372713, v138
	v_mul_f32_e32 v139, v138, v139
	v_fma_f32 v139, v138, v139, v138
	v_mul_f32_e32 v139, 0x3f4c422a, v139
	v_add_f32_e32 v139, v139, v139
	v_mul_f32_e32 v139, 0x3fb8aa3b, v139
	v_exp_f32_e32 v139, v139
	v_mul_f32_e32 v138, 0.5, v138
	v_add_f32_e32 v139, 1.0, v139
	v_div_scale_f32 v142, s[26:27], v139, v139, 2.0
	v_rcp_f32_e32 v143, v142
	s_nop 0
	v_fma_f32 v144, -v142, v143, 1.0
	v_fmac_f32_e32 v143, v144, v143
	v_div_scale_f32 v144, vcc, 2.0, v139, 2.0
	v_mul_f32_e32 v145, v144, v143
	v_fma_f32 v146, -v142, v145, v144
	v_fmac_f32_e32 v145, v146, v143
	v_fma_f32 v142, -v142, v145, v144
	v_div_fmas_f32 v142, v142, v143, v145
	v_div_fixup_f32 v139, v142, v139, 2.0
	v_sub_f32_e32 v139, 1.0, v139
	v_add_f32_e32 v139, 1.0, v139
	v_mul_f32_e32 v169, v138, v139
	ds_write_b32 v222, v169 offset:55296
	v_lshl_add_u32 v138, v223, 2, s3
	ds_read_b32 v138, v138
	v_pk_fma_f32 v[146:147], v[108:109], v[132:133], v[20:21] neg_lo:[0,0,1] neg_hi:[0,0,1]
	v_pk_fma_f32 v[20:21], v[108:109], v[132:133], v[20:21] op_sel_hi:[1,0,1]
	s_waitcnt lgkmcnt(0)
	v_fma_f32 v138, v200, v138, v140
	v_mul_f32_e32 v139, 0x3d372713, v138
	v_mul_f32_e32 v139, v138, v139
	v_fma_f32 v139, v138, v139, v138
	v_mul_f32_e32 v139, 0x3f4c422a, v139
	v_add_f32_e32 v139, v139, v139
	v_mul_f32_e32 v139, 0x3fb8aa3b, v139
	v_exp_f32_e32 v139, v139
	v_mul_f32_e32 v138, 0.5, v138
	v_mov_b32_e32 v147, v21
	v_add_f32_e32 v139, 1.0, v139
	v_div_scale_f32 v140, s[26:27], v139, v139, 2.0
	v_rcp_f32_e32 v142, v140
	s_nop 0
	v_fma_f32 v143, -v140, v142, 1.0
	v_fmac_f32_e32 v142, v143, v142
	v_div_scale_f32 v143, vcc, 2.0, v139, 2.0
	v_mul_f32_e32 v144, v143, v142
	v_fma_f32 v145, -v140, v144, v143
	v_fmac_f32_e32 v144, v145, v142
	v_fma_f32 v140, -v140, v144, v143
	v_div_fmas_f32 v140, v140, v142, v144
	v_div_fixup_f32 v139, v140, v139, 2.0
	v_sub_f32_e32 v139, 1.0, v139
	v_add_f32_e32 v139, 1.0, v139
	v_mul_f32_e32 v170, v138, v139
	ds_write_b32 v224, v170 offset:55296
	v_lshl_add_u32 v138, v225, 2, s3
	ds_read_b32 v138, v138
	s_mov_b32 s3, 0x10d00000
	s_waitcnt lgkmcnt(0)
; #define LAS __attribute__((address_space(3)))
; #define LDS_WAIT() asm volatile("s_waitcnt lgkmcnt(0)" ::: "memory")
; __device__ __forceinline__ float gelu_tanh(float y) {
;     const float x = 0.7978845608028654f * (y + 0.044715f * y * y * y);
;     const float e = __expf(2.0f * x);
;     const float th = 1.0f - 2.0f / (e + 1.0f);
;     return 0.5f * y * (1.0f + th);
; }
; __device__ __forceinline__ float sigmoidf(float s) { return 1.0f / (1.0f + __expf(-s)); }
; template <bool SAMPLE>
; __device__ __forceinline__ void ssm_item(kp_t kp, LAS unsigned char* lds, int l, int item, const bf16_t* Z, float* YM, int tid, int lane, int wave) {
;     ...
;         for (int j = 0; j < 4; ++j) { const int t = wave * 16 + fq * 4 + j; float y = acc[j] + Dv * U[t * 16 + fr]; y = gelu_tanh(y); yv[j] = y; Yb[t * 16 + fr] = y; }
;         LDS_WAIT();
; #pragma unroll
;         for (int j = 0; j < 4; ++j) { const int t = wave * 16 + fq * 4 + j; const LAS f32x4* yp = (const LAS f32x4*)(Yb + t * 16); float s = 0.f;
; #pragma unroll
;             for (int q = 0; q < 4; ++q) { const f32x4 v = yp[q]; s += (v[0] * wg[4 * q] + v[1] * wg[4 * q + 1]) + (v[2] * wg[4 * q + 2] + v[3] * wg[4 * q + 3]); }
;             YM[(tok0 + t) * DM + g * 16 + fr] = yv[j] * sigmoidf(s); }
	v_fmac_f32_e32 v141, v200, v138
	v_mul_f32_e32 v138, 0x3d372713, v141
	v_mul_f32_e32 v138, v141, v138
	v_fma_f32 v138, v141, v138, v141
	v_mul_f32_e32 v138, 0x3f4c422a, v138
	v_add_f32_e32 v138, v138, v138
	v_mul_f32_e32 v138, 0x3fb8aa3b, v138
	v_exp_f32_e32 v138, v138
	s_nop 0
	v_add_f32_e32 v138, 1.0, v138
	v_div_scale_f32 v139, s[26:27], v138, v138, 2.0
	v_rcp_f32_e32 v140, v139
	s_nop 0
	v_fma_f32 v142, -v139, v140, 1.0
	v_fmac_f32_e32 v140, v142, v140
	v_div_scale_f32 v142, vcc, 2.0, v138, 2.0
	v_mul_f32_e32 v143, v142, v140
	v_fma_f32 v144, -v139, v143, v142
	v_fmac_f32_e32 v143, v144, v140
	v_fma_f32 v139, -v139, v143, v142
	v_div_fmas_f32 v139, v139, v140, v143
	v_div_fixup_f32 v138, v139, v138, 2.0
	v_sub_f32_e32 v138, 1.0, v138
	v_mul_f32_e32 v139, 0.5, v141
	v_add_f32_e32 v138, 1.0, v138
	v_mul_f32_e32 v171, v139, v138
	ds_write_b32 v226, v171 offset:55296
	s_waitcnt lgkmcnt(0)
	ds_read_b128 v[138:141], v228 offset:55296
	ds_read_b128 v[142:145], v228 offset:55312
	ds_read_b128 v[160:163], v228 offset:55328
	ds_read_b128 v[164:167], v228 offset:55344
	s_waitcnt lgkmcnt(3)
	v_mul_f32_e32 v139, v202, v139
	v_fmac_f32_e32 v139, v201, v138
	v_mul_f32_e32 v138, v204, v141
	v_fmac_f32_e32 v138, v203, v140
	v_add_f32_e32 v138, v139, v138
	s_waitcnt lgkmcnt(2)
	v_mul_f32_e32 v139, v206, v143
	v_mul_f32_e32 v140, v208, v145
	v_fmac_f32_e32 v139, v205, v142
	v_fmac_f32_e32 v140, v207, v144
	v_add_f32_e32 v138, 0, v138
	v_add_f32_e32 v139, v139, v140
	v_add_f32_e32 v138, v138, v139
	s_waitcnt lgkmcnt(1)
	v_mul_f32_e32 v139, v210, v161
	v_mul_f32_e32 v140, v212, v163
	v_fmac_f32_e32 v139, v209, v160
	v_fmac_f32_e32 v140, v211, v162
	v_add_f32_e32 v139, v139, v140
	v_add_f32_e32 v138, v138, v139
	s_waitcnt lgkmcnt(0)
	v_mul_f32_e32 v139, v214, v165
	v_mul_f32_e32 v140, v216, v167
	v_fmac_f32_e32 v139, v213, v164
	v_fmac_f32_e32 v140, v215, v166
	v_add_f32_e32 v139, v139, v140
	v_add_f32_e32 v138, v138, v139
	v_mul_f32_e32 v138, 0xbfb8aa3b, v138
	v_exp_f32_e32 v138, v138
	s_nop 0
	v_add_f32_e32 v172, 1.0, v138
	v_div_scale_f32 v138, s[26:27], v172, v172, 1.0
	v_rcp_f32_e32 v142, v138
	s_nop 0
	v_fma_f32 v20, -v138, v142, 1.0
	v_fmac_f32_e32 v142, v20, v142
	v_div_scale_f32 v20, vcc, 1.0, v172, 1.0
	v_mul_f32_e32 v21, v20, v142
	v_fma_f32 v132, -v138, v21, v20
	v_fmac_f32_e32 v21, v132, v142
	v_fma_f32 v20, -v138, v21, v20
	ds_read_b128 v[138:141], v229 offset:55296
	v_div_fmas_f32 v20, v20, v142, v21
	ds_read_b128 v[142:145], v229 offset:55312
	ds_read_b128 v[160:163], v229 offset:55328
	ds_read_b128 v[164:167], v229 offset:55344
	v_div_fixup_f32 v20, v20, v172, 1.0
	s_waitcnt lgkmcnt(3)
	v_mul_f32_e32 v21, v202, v139
	v_mul_f32_e32 v132, v204, v141
	v_fmac_f32_e32 v21, v201, v138
	v_fmac_f32_e32 v132, v203, v140
	v_add_f32_e32 v21, v21, v132
	s_waitcnt lgkmcnt(2)
	v_mul_f32_e32 v132, v206, v143
	v_mul_f32_e32 v133, v208, v145
	v_fmac_f32_e32 v132, v205, v142
	v_fmac_f32_e32 v133, v207, v144
	v_add_f32_e32 v21, 0, v21
	v_add_f32_e32 v132, v132, v133
	v_add_f32_e32 v21, v21, v132
	s_waitcnt lgkmcnt(1)
	v_mul_f32_e32 v132, v210, v161
	v_mul_f32_e32 v133, v212, v163
	v_fmac_f32_e32 v132, v209, v160
	v_fmac_f32_e32 v133, v211, v162
	v_add_f32_e32 v132, v132, v133
	v_add_f32_e32 v21, v21, v132
	s_waitcnt lgkmcnt(0)
	v_mul_f32_e32 v132, v214, v165
	v_mul_f32_e32 v133, v216, v167
	v_fmac_f32_e32 v132, v213, v164
	v_fmac_f32_e32 v133, v215, v166
	v_add_f32_e32 v132, v132, v133
	v_add_f32_e32 v21, v21, v132
	v_mul_f32_e32 v21, 0xbfb8aa3b, v21
	v_exp_f32_e32 v132, v21
	v_mul_f32_e32 v138, v168, v20
	v_lshl_add_u64 v[20:21], v[136:137], 0, s[20:21]
	s_add_u32 s20, s20, 0x100000
	v_add_f32_e32 v168, 1.0, v132
	v_div_scale_f32 v142, s[26:27], v168, v168, 1.0
	v_rcp_f32_e32 v172, v142
	v_add_co_u32_e32 v132, vcc, s3, v20
	s_mov_b32 s3, 0x10d02000
	s_nop 0
	v_addc_co_u32_e32 v133, vcc, 0, v21, vcc
	s_waitcnt vmcnt(0)
; #define LAS __attribute__((address_space(3)))
; __device__ __forceinline__ f32x4 ldbf4(const bf16_t* p) { const u32x2 w = *(const u32x2*)p; return (f32x4){bf_lo(w.x), bf_hi(w.x), bf_lo(w.y), bf_hi(w.y)}; }
; __device__ __forceinline__ float sigmoidf(float s) { return 1.0f / (1.0f + __expf(-s)); }
; template <bool SAMPLE>
; __device__ __forceinline__ void ssm_item(kp_t kp, LAS unsigned char* lds, int l, int item, const bf16_t* Z, float* YM, int tid, int lane, int wave) {
;     ...
;     for (int ch = 0; ch < NCH; ++ch) {
;         const size_t tok0 = row0 + ch * 128;
;         LAS float* U = Ub + (ch & 1) * 2048;
;         *(LAS f32x4*)(U + tid * 4) = ureg;
;         if (ch < NCH - 1) ureg = ldbf4(zsrc + (size_t)(ch + 1) * 128 * INW);
;     ...
;         for (int j = 0; j < 4; ++j) { const int t = wave * 16 + fq * 4 + j; const LAS f32x4* yp = (const LAS f32x4*)(Yb + t * 16); float s = 0.f;
; #pragma unroll
;             for (int q = 0; q < 4; ++q) { const f32x4 v = yp[q]; s += (v[0] * wg[4 * q] + v[1] * wg[4 * q + 1]) + (v[2] * wg[4 * q + 2] + v[3] * wg[4 * q + 3]); }
;             YM[(tok0 + t) * DM + g * 16 + fr] = yv[j] * sigmoidf(s); }
	v_lshlrev_b32_e32 v0, 16, v2
	v_and_b32_e32 v1, 0xffff0000, v2
	v_lshlrev_b32_e32 v2, 16, v3
	v_and_b32_e32 v3, 0xffff0000, v3
	global_store_dword v[132:133], v138, off
	v_fma_f32 v132, -v142, v172, 1.0
	v_fmac_f32_e32 v172, v132, v172
	v_div_scale_f32 v132, vcc, 1.0, v168, 1.0
	v_mul_f32_e32 v133, v132, v172
	v_fma_f32 v138, -v142, v133, v132
	v_fmac_f32_e32 v133, v138, v172
	ds_read_b128 v[138:141], v230 offset:55296
	v_fma_f32 v132, -v142, v133, v132
	ds_read_b128 v[142:145], v230 offset:55312
	ds_read_b128 v[160:163], v230 offset:55328
	ds_read_b128 v[164:167], v230 offset:55344
	v_div_fmas_f32 v132, v132, v172, v133
	v_div_fixup_f32 v132, v132, v168, 1.0
	s_waitcnt lgkmcnt(3)
	v_mul_f32_e32 v139, v202, v139
	v_fmac_f32_e32 v139, v201, v138
	v_mul_f32_e32 v138, v204, v141
	v_fmac_f32_e32 v138, v203, v140
	v_add_f32_e32 v138, v139, v138
	s_waitcnt lgkmcnt(2)
	v_mul_f32_e32 v139, v206, v143
	v_mul_f32_e32 v140, v208, v145
	v_fmac_f32_e32 v139, v205, v142
	v_fmac_f32_e32 v140, v207, v144
	v_add_f32_e32 v138, 0, v138
	v_add_f32_e32 v139, v139, v140
	v_add_f32_e32 v138, v138, v139
	s_waitcnt lgkmcnt(1)
	v_mul_f32_e32 v139, v210, v161
	v_mul_f32_e32 v140, v212, v163
	v_fmac_f32_e32 v139, v209, v160
	v_fmac_f32_e32 v140, v211, v162
	v_add_f32_e32 v139, v139, v140
	v_add_f32_e32 v138, v138, v139
	s_waitcnt lgkmcnt(0)
	v_mul_f32_e32 v139, v214, v165
	v_mul_f32_e32 v140, v216, v167
	v_fmac_f32_e32 v139, v213, v164
	v_fmac_f32_e32 v140, v215, v166
	v_add_f32_e32 v139, v139, v140
	v_add_f32_e32 v138, v138, v139
	v_mul_f32_e32 v138, 0xbfb8aa3b, v138
	v_exp_f32_e32 v138, v138
	v_mul_f32_e32 v139, v169, v132
	v_add_co_u32_e32 v132, vcc, s3, v20
	v_add_f32_e32 v168, 1.0, v138
	v_div_scale_f32 v142, s[26:27], v168, v168, 1.0
	v_rcp_f32_e32 v169, v142
	v_addc_co_u32_e32 v133, vcc, 0, v21, vcc
	global_store_dword v[132:133], v139, off
	v_fma_f32 v132, -v142, v169, 1.0
	v_fmac_f32_e32 v169, v132, v169
	v_div_scale_f32 v132, vcc, 1.0, v168, 1.0
	v_mul_f32_e32 v133, v132, v169
	v_fma_f32 v138, -v142, v133, v132
	v_fmac_f32_e32 v133, v138, v169
	ds_read_b128 v[138:141], v231 offset:55296
	v_fma_f32 v132, -v142, v133, v132
	ds_read_b128 v[142:145], v231 offset:55312
	ds_read_b128 v[160:163], v231 offset:55328
	ds_read_b128 v[164:167], v231 offset:55344
	v_div_fmas_f32 v132, v132, v169, v133
	v_div_fixup_f32 v132, v132, v168, 1.0
	s_waitcnt lgkmcnt(3)
	v_mul_f32_e32 v139, v202, v139
	v_fmac_f32_e32 v139, v201, v138
	v_mul_f32_e32 v138, v204, v141
	v_fmac_f32_e32 v138, v203, v140
	v_add_f32_e32 v138, v139, v138
	s_waitcnt lgkmcnt(2)
	v_mul_f32_e32 v139, v206, v143
	v_mul_f32_e32 v140, v208, v145
	v_fmac_f32_e32 v139, v205, v142
	v_fmac_f32_e32 v140, v207, v144
	v_add_f32_e32 v138, 0, v138
	v_add_f32_e32 v139, v139, v140
	v_add_f32_e32 v138, v138, v139
	s_waitcnt lgkmcnt(1)
	v_mul_f32_e32 v139, v210, v161
	v_mul_f32_e32 v140, v212, v163
	v_fmac_f32_e32 v139, v209, v160
	v_fmac_f32_e32 v140, v211, v162
	v_add_f32_e32 v139, v139, v140
	v_add_f32_e32 v138, v138, v139
	s_waitcnt lgkmcnt(0)
	v_mul_f32_e32 v139, v214, v165
	v_mul_f32_e32 v140, v216, v167
	v_fmac_f32_e32 v139, v213, v164
	v_fmac_f32_e32 v140, v215, v166
	v_add_f32_e32 v139, v139, v140
	v_add_f32_e32 v138, v138, v139
	v_mul_f32_e32 v138, 0xbfb8aa3b, v138
	v_exp_f32_e32 v138, v138
	s_mov_b32 s3, 0x10d04000
	v_mul_f32_e32 v139, v170, v132
	v_add_co_u32_e32 v132, vcc, s3, v20
	v_add_f32_e32 v138, 1.0, v138
	v_div_scale_f32 v140, s[26:27], v138, v138, 1.0
	v_rcp_f32_e32 v141, v140
	v_addc_co_u32_e32 v133, vcc, 0, v21, vcc
	global_store_dword v[132:133], v139, off
	v_fma_f32 v132, -v140, v141, 1.0
	v_fmac_f32_e32 v141, v132, v141
	v_div_scale_f32 v132, vcc, 1.0, v138, 1.0
	v_mul_f32_e32 v133, v132, v141
	v_fma_f32 v139, -v140, v133, v132
	v_fmac_f32_e32 v133, v139, v141
	v_fma_f32 v132, -v140, v133, v132
	v_div_fmas_f32 v132, v132, v141, v133
	s_mov_b32 s3, 0x10d06000
	v_div_fixup_f32 v132, v132, v138, 1.0
	v_add_co_u32_e32 v20, vcc, s3, v20
	v_mul_f32_e32 v132, v171, v132
	s_nop 0
	v_addc_co_u32_e32 v21, vcc, 0, v21, vcc
	global_store_dword v[20:21], v132, off
	s_waitcnt lgkmcnt(0)
	s_addc_u32 s21, s21, 0
	s_addk_i32 s23, 0x800
	s_mov_b64 s[26:27], 0xa0000
	v_pk_add_f32 v[132:133], v[22:23], v[146:147]
	s_cmp_eq_u32 s20, 0x1000000
	v_lshl_add_u64 v[134:135], v[134:135], 0, s[26:27]
	s_cbranch_scc1 .LBB0_103
